# grid barrier: every workgroup (leaders too) waits on the cumulative top arrival counter; generation words no longer published
# speedup vs baseline: 1.0149x; 1.0007x over previous
; __device__ __forceinline__ unsigned xb_ld(unsigned* p)              { return __hip_atomic_load(p, __ATOMIC_RELAXED, __HIP_MEMORY_SCOPE_AGENT); }
; __device__ __forceinline__ unsigned xb_add(unsigned* p, unsigned v) { return __hip_atomic_fetch_add(p, v, __ATOMIC_RELAXED, __HIP_MEMORY_SCOPE_AGENT); }
; #define XB_SPIN(cond, bar) do { unsigned _sp = 0; while (cond) { if (XB_SLEEP) __builtin_amdgcn_s_sleep(1); \
;     if ((++_sp & 255u) == 0u) { if (xb_ld(&(bar)[XB_TMO])) break; if (_sp > XB_SPIN_CAP) { atomicAdd(&(bar)[XB_TMO], 1u); break; } } } } while (0)
; __device__ __forceinline__ void xcd_barrier(const XcdBarrier& b) {
;     ...
;         const unsigned old = xb_add(&bar[XB_XSUB(b.x)], 1u);
;         const unsigned gen = old / nloc;
;         if (old + 1u == (gen + 1u) * nloc) {
;             __builtin_amdgcn_fence(__ATOMIC_RELEASE, "agent");
;             asm volatile("s_waitcnt vmcnt(0)" ::: "memory");
;             const unsigned og = xb_add(&bar[XB_TOP], 1u);
;             const unsigned tg = og / nx;
;             if (og + 1u == (tg + 1u) * nx) xb_add(&bar[XB_TOPGEN], 1u);
;             else XB_SPIN(xb_ld(&bar[XB_TOPGEN]) == tg, bar);
;             __builtin_amdgcn_fence(__ATOMIC_ACQUIRE, "agent");
;             xb_add(&bar[XB_XGEN(b.x)], 1u);
;             asm volatile("s_waitcnt vmcnt(0)" ::: "memory");
;         } else {
;             XB_SPIN(xb_ld(&bar[XB_XGEN(b.x)]) == gen, bar);
.LBB0_100:
	s_or_b64 exec, exec, s[24:25]
	v_cvt_f32_u32_e32 v4, v2
	s_waitcnt vmcnt(0)
	v_readfirstlane_b32 s19, v3
	v_sub_u32_e32 v3, 0, v2
	v_rcp_iflag_f32_e32 v4, v4
	v_add_u32_e32 v5, s19, v1
	v_mul_f32_e32 v4, 0x4f7ffffe, v4
	v_cvt_u32_f32_e32 v4, v4
	v_mul_lo_u32 v1, v3, v4
	v_mul_hi_u32 v1, v4, v1
	v_add_u32_e32 v1, v4, v1
	v_mul_hi_u32 v1, v5, v1
	v_mul_lo_u32 v3, v1, v2
	v_sub_u32_e32 v3, v5, v3
	v_add_u32_e32 v4, 1, v1
	v_cmp_ge_u32_e32 vcc, v3, v2
	s_nop 1
	v_cndmask_b32_e32 v1, v1, v4, vcc
	v_sub_u32_e32 v4, v3, v2
	v_cndmask_b32_e32 v3, v3, v4, vcc
	v_add_u32_e32 v4, 1, v1
	v_cmp_ge_u32_e32 vcc, v3, v2
	v_add_u32_e32 v3, 1, v5
	s_nop 0
	v_cndmask_b32_e32 v1, v1, v4, vcc
	v_mul_lo_u32 v4, v2, v1
	v_add_u32_e32 v2, v4, v2
	v_cmp_ne_u32_e32 vcc, v3, v2
	s_and_saveexec_b64 s[22:23], vcc
	s_xor_b64 s[22:23], exec, s[22:23]
	s_cbranch_execz .LBB0_114
	s_waitcnt lgkmcnt(0)
	v_add_u32_e32 v1, 1, v1
	v_mul_lo_u32 v1, v1, v0
	s_add_u32 s30, s86, 0x3400
	s_addc_u32 s31, s87, 0
	v_mov_b32_e32 v0, 0
	global_load_dword v0, v0, s[30:31] sc1
	s_waitcnt vmcnt(0)
	v_cmp_lt_u32_e32 vcc, v0, v1
	s_and_saveexec_b64 s[24:25], vcc
	s_cbranch_execz .LBB0_113
	s_add_u32 s26, s80, 0x60200
	s_addc_u32 s27, s81, 0
	s_mov_b32 s19, 1
	s_mov_b64 s[34:35], 0
	v_mov_b32_e32 v0, 0
	s_branch .LBB0_104

; __device__ __forceinline__ unsigned xb_ld(unsigned* p)              { return __hip_atomic_load(p, __ATOMIC_RELAXED, __HIP_MEMORY_SCOPE_AGENT); }
; #define XB_SPIN(cond, bar) do { unsigned _sp = 0; while (cond) { if (XB_SLEEP) __builtin_amdgcn_s_sleep(1); \
;     if ((++_sp & 255u) == 0u) { if (xb_ld(&(bar)[XB_TMO])) break; if (_sp > XB_SPIN_CAP) { atomicAdd(&(bar)[XB_TMO], 1u); break; } } } } while (0)
; __device__ __forceinline__ void xcd_barrier(const XcdBarrier& b) {
;     ...
;             XB_SPIN(xb_ld(&bar[XB_XGEN(b.x)]) == gen, bar);
.LBB0_108:
	global_load_dword v2, v0, s[30:31] sc1
	s_add_i32 s19, s19, 1
	s_mov_b64 s[40:41], -1
	s_waitcnt vmcnt(0)
	v_cmp_ge_u32_e32 vcc, v2, v1
	s_orn2_b64 s[38:39], vcc, exec
	s_branch .LBB0_103

; __device__ __forceinline__ unsigned xb_ld(unsigned* p)              { return __hip_atomic_load(p, __ATOMIC_RELAXED, __HIP_MEMORY_SCOPE_AGENT); }
; __device__ __forceinline__ unsigned xb_add(unsigned* p, unsigned v) { return __hip_atomic_fetch_add(p, v, __ATOMIC_RELAXED, __HIP_MEMORY_SCOPE_AGENT); }
; #define XB_SPIN(cond, bar) do { unsigned _sp = 0; while (cond) { if (XB_SLEEP) __builtin_amdgcn_s_sleep(1); \
;     if ((++_sp & 255u) == 0u) { if (xb_ld(&(bar)[XB_TMO])) break; if (_sp > XB_SPIN_CAP) { atomicAdd(&(bar)[XB_TMO], 1u); break; } } } } while (0)
; __device__ __forceinline__ void xcd_barrier(const XcdBarrier& b) {
;     ...
;         if (old + 1u == (gen + 1u) * nloc) {
;             __builtin_amdgcn_fence(__ATOMIC_RELEASE, "agent");
;             asm volatile("s_waitcnt vmcnt(0)" ::: "memory");
;             const unsigned og = xb_add(&bar[XB_TOP], 1u);
;             const unsigned tg = og / nx;
;             if (og + 1u == (tg + 1u) * nx) xb_add(&bar[XB_TOPGEN], 1u);
;             else XB_SPIN(xb_ld(&bar[XB_TOPGEN]) == tg, bar);
.LBB0_117:
	s_or_b64 exec, exec, s[24:25]
	v_cvt_f32_u32_e32 v3, v0
	s_waitcnt vmcnt(0)
	v_readfirstlane_b32 s19, v2
	s_add_u32 s24, s80, 0x63500
	s_addc_u32 s25, s81, 0
	v_rcp_iflag_f32_e32 v3, v3
	v_add_u32_e32 v1, s19, v1
	v_add_u32_e32 v4, 1, v1
	s_mov_b64 s[26:27], 0
	v_mul_f32_e32 v2, 0x4f7ffffe, v3
	v_cvt_u32_f32_e32 v2, v2
	v_sub_u32_e32 v3, 0, v0
	v_mul_lo_u32 v3, v3, v2
	v_mul_hi_u32 v3, v2, v3
	v_add_u32_e32 v2, v2, v3
	v_mul_hi_u32 v2, v1, v2
	v_mul_lo_u32 v3, v2, v0
	v_sub_u32_e32 v1, v1, v3
	v_add_u32_e32 v5, 1, v2
	v_cmp_ge_u32_e32 vcc, v1, v0
	v_sub_u32_e32 v3, v1, v0
	s_nop 0
	v_cndmask_b32_e32 v2, v2, v5, vcc
	v_cndmask_b32_e32 v1, v1, v3, vcc
	v_add_u32_e32 v3, 1, v2
	v_cmp_ge_u32_e32 vcc, v1, v0
	s_nop 1
	v_cndmask_b32_e32 v2, v2, v3, vcc
	v_mul_lo_u32 v1, v0, v2
	v_add_u32_e32 v0, v1, v0
	v_cmp_ne_u32_e32 vcc, v4, v0
	v_mov_b32_e32 v254, v0
	v_mov_b64_e32 v[0:1], s[24:25]
	s_and_saveexec_b64 s[22:23], vcc
	s_cbranch_execz .LBB0_129
	v_mov_b32_e32 v0, 0
	s_sub_u32 s98, s24, 0x100
	s_subb_u32 s99, s25, 0
	global_load_dword v1, v0, s[98:99] sc1
	s_mov_b64 s[34:35], 0
	s_waitcnt vmcnt(0)
	v_cmp_lt_u32_e32 vcc, v1, v254
	s_and_saveexec_b64 s[30:31], vcc
	s_cbranch_execz .LBB0_128
	s_add_u32 s26, s80, 0x60200
	s_addc_u32 s27, s81, 0
	s_mov_b32 s19, 1
	s_branch .LBB0_121

; __device__ __forceinline__ unsigned xb_ld(unsigned* p)              { return __hip_atomic_load(p, __ATOMIC_RELAXED, __HIP_MEMORY_SCOPE_AGENT); }
; #define XB_SPIN(cond, bar) do { unsigned _sp = 0; while (cond) { if (XB_SLEEP) __builtin_amdgcn_s_sleep(1); \
;     if ((++_sp & 255u) == 0u) { if (xb_ld(&(bar)[XB_TMO])) break; if (_sp > XB_SPIN_CAP) { atomicAdd(&(bar)[XB_TMO], 1u); break; } } } } while (0)
; __device__ __forceinline__ void xcd_barrier(const XcdBarrier& b) {
;     ...
;             else XB_SPIN(xb_ld(&bar[XB_TOPGEN]) == tg, bar);
.LBB0_125:
	global_load_dword v1, v0, s[98:99] sc1
	s_add_i32 s19, s19, 1
	s_mov_b64 s[38:39], -1
	s_waitcnt vmcnt(0)
	v_cmp_ge_u32_e32 vcc, v1, v254
	s_orn2_b64 s[42:43], vcc, exec
	s_branch .LBB0_120

; __device__ __forceinline__ unsigned xb_add(unsigned* p, unsigned v) { return __hip_atomic_fetch_add(p, v, __ATOMIC_RELAXED, __HIP_MEMORY_SCOPE_AGENT); }
; __device__ __forceinline__ void xcd_barrier(const XcdBarrier& b) {
;     ...
;             __builtin_amdgcn_fence(__ATOMIC_ACQUIRE, "agent");
;             xb_add(&bar[XB_XGEN(b.x)], 1u);
.LBB0_131:
	s_or_b64 exec, exec, s[22:23]
	s_mov_b64 s[22:23], exec
	v_mbcnt_lo_u32_b32 v0, s22, 0
	v_mbcnt_hi_u32_b32 v0, s23, v0
	v_cmp_eq_u32_e32 vcc, 0, v0
	s_waitcnt vmcnt(0)
	buffer_inv sc1
	s_and_saveexec_b64 s[24:25], vcc
	s_cbranch_execz .LBB0_133
	s_bcnt1_i32_b64 s19, s[22:23]
	v_mov_b32_e32 v0, 0x2000
	v_mov_b32_e32 v1, s19
.LBB0_133:
	s_or_b64 exec, exec, s[24:25]
	s_waitcnt vmcnt(0)

; __device__ __forceinline__ unsigned xb_ld(unsigned* p)              { return __hip_atomic_load(p, __ATOMIC_RELAXED, __HIP_MEMORY_SCOPE_AGENT); }
; __device__ __forceinline__ unsigned xb_add(unsigned* p, unsigned v) { return __hip_atomic_fetch_add(p, v, __ATOMIC_RELAXED, __HIP_MEMORY_SCOPE_AGENT); }
; #define XB_SPIN(cond, bar) do { unsigned _sp = 0; while (cond) { if (XB_SLEEP) __builtin_amdgcn_s_sleep(1); \
;     if ((++_sp & 255u) == 0u) { if (xb_ld(&(bar)[XB_TMO])) break; if (_sp > XB_SPIN_CAP) { atomicAdd(&(bar)[XB_TMO], 1u); break; } } } } while (0)
; __device__ __forceinline__ void xcd_barrier(const XcdBarrier& b) {
;     ...
;         const unsigned old = xb_add(&bar[XB_XSUB(b.x)], 1u);
;         const unsigned gen = old / nloc;
;         if (old + 1u == (gen + 1u) * nloc) {
;             __builtin_amdgcn_fence(__ATOMIC_RELEASE, "agent");
;             asm volatile("s_waitcnt vmcnt(0)" ::: "memory");
;             const unsigned og = xb_add(&bar[XB_TOP], 1u);
;             const unsigned tg = og / nx;
;             if (og + 1u == (tg + 1u) * nx) xb_add(&bar[XB_TOPGEN], 1u);
;             else XB_SPIN(xb_ld(&bar[XB_TOPGEN]) == tg, bar);
;             __builtin_amdgcn_fence(__ATOMIC_ACQUIRE, "agent");
;             xb_add(&bar[XB_XGEN(b.x)], 1u);
;             asm volatile("s_waitcnt vmcnt(0)" ::: "memory");
;         } else {
;             XB_SPIN(xb_ld(&bar[XB_XGEN(b.x)]) == gen, bar);
.LBB0_183:
	s_or_b64 exec, exec, s[20:21]
	v_cvt_f32_u32_e32 v4, v2
	s_waitcnt vmcnt(0)
	v_readfirstlane_b32 s18, v3
	v_sub_u32_e32 v3, 0, v2
	v_rcp_iflag_f32_e32 v4, v4
	v_add_u32_e32 v5, s18, v1
	v_mul_f32_e32 v4, 0x4f7ffffe, v4
	v_cvt_u32_f32_e32 v4, v4
	v_mul_lo_u32 v1, v3, v4
	v_mul_hi_u32 v1, v4, v1
	v_add_u32_e32 v1, v4, v1
	v_mul_hi_u32 v1, v5, v1
	v_mul_lo_u32 v3, v1, v2
	v_sub_u32_e32 v3, v5, v3
	v_add_u32_e32 v4, 1, v1
	v_cmp_ge_u32_e32 vcc, v3, v2
	s_nop 1
	v_cndmask_b32_e32 v1, v1, v4, vcc
	v_sub_u32_e32 v4, v3, v2
	v_cndmask_b32_e32 v3, v3, v4, vcc
	v_add_u32_e32 v4, 1, v1
	v_cmp_ge_u32_e32 vcc, v3, v2
	v_add_u32_e32 v3, 1, v5
	s_nop 0
	v_cndmask_b32_e32 v1, v1, v4, vcc
	v_mul_lo_u32 v4, v2, v1
	v_add_u32_e32 v2, v4, v2
	v_cmp_ne_u32_e32 vcc, v3, v2
	s_and_saveexec_b64 s[18:19], vcc
	s_xor_b64 s[18:19], exec, s[18:19]
	s_cbranch_execz .LBB0_197
	s_waitcnt lgkmcnt(0)
	v_add_u32_e32 v1, 1, v1
	v_mul_lo_u32 v1, v1, v0
	s_add_u32 s24, s86, 0x3400
	s_addc_u32 s25, s87, 0
	v_mov_b32_e32 v0, 0
	global_load_dword v0, v0, s[24:25] sc1
	s_waitcnt vmcnt(0)
	v_cmp_lt_u32_e32 vcc, v0, v1
	s_and_saveexec_b64 s[20:21], vcc
	s_cbranch_execz .LBB0_196
	s_add_u32 s22, s80, 0x60200
	s_addc_u32 s23, s81, 0
	s_mov_b32 s33, 1
	s_mov_b64 s[26:27], 0
	v_mov_b32_e32 v0, 0
	s_branch .LBB0_187

; __device__ __forceinline__ unsigned xb_ld(unsigned* p)              { return __hip_atomic_load(p, __ATOMIC_RELAXED, __HIP_MEMORY_SCOPE_AGENT); }
; #define XB_SPIN(cond, bar) do { unsigned _sp = 0; while (cond) { if (XB_SLEEP) __builtin_amdgcn_s_sleep(1); \
;     if ((++_sp & 255u) == 0u) { if (xb_ld(&(bar)[XB_TMO])) break; if (_sp > XB_SPIN_CAP) { atomicAdd(&(bar)[XB_TMO], 1u); break; } } } } while (0)
; __device__ __forceinline__ void xcd_barrier(const XcdBarrier& b) {
;     ...
;             XB_SPIN(xb_ld(&bar[XB_XGEN(b.x)]) == gen, bar);
.LBB0_191:
	global_load_dword v2, v0, s[24:25] sc1
	s_add_i32 s33, s33, 1
	s_mov_b64 s[36:37], -1
	s_waitcnt vmcnt(0)
	v_cmp_ge_u32_e32 vcc, v2, v1
	s_orn2_b64 s[34:35], vcc, exec
	s_branch .LBB0_186

; __device__ __forceinline__ unsigned xb_ld(unsigned* p)              { return __hip_atomic_load(p, __ATOMIC_RELAXED, __HIP_MEMORY_SCOPE_AGENT); }
; __device__ __forceinline__ unsigned xb_add(unsigned* p, unsigned v) { return __hip_atomic_fetch_add(p, v, __ATOMIC_RELAXED, __HIP_MEMORY_SCOPE_AGENT); }
; #define XB_SPIN(cond, bar) do { unsigned _sp = 0; while (cond) { if (XB_SLEEP) __builtin_amdgcn_s_sleep(1); \
;     if ((++_sp & 255u) == 0u) { if (xb_ld(&(bar)[XB_TMO])) break; if (_sp > XB_SPIN_CAP) { atomicAdd(&(bar)[XB_TMO], 1u); break; } } } } while (0)
; __device__ __forceinline__ void xcd_barrier(const XcdBarrier& b) {
;     ...
;         if (old + 1u == (gen + 1u) * nloc) {
;             __builtin_amdgcn_fence(__ATOMIC_RELEASE, "agent");
;             asm volatile("s_waitcnt vmcnt(0)" ::: "memory");
;             const unsigned og = xb_add(&bar[XB_TOP], 1u);
;             const unsigned tg = og / nx;
;             if (og + 1u == (tg + 1u) * nx) xb_add(&bar[XB_TOPGEN], 1u);
;             else XB_SPIN(xb_ld(&bar[XB_TOPGEN]) == tg, bar);
.LBB0_200:
	s_or_b64 exec, exec, s[20:21]
	v_cvt_f32_u32_e32 v3, v0
	s_waitcnt vmcnt(0)
	v_readfirstlane_b32 s18, v2
	s_add_u32 s20, s80, 0x63500
	s_addc_u32 s21, s81, 0
	v_rcp_iflag_f32_e32 v3, v3
	v_add_u32_e32 v1, s18, v1
	v_add_u32_e32 v4, 1, v1
	s_mov_b64 s[22:23], 0
	v_mul_f32_e32 v2, 0x4f7ffffe, v3
	v_cvt_u32_f32_e32 v2, v2
	v_sub_u32_e32 v3, 0, v0
	v_mul_lo_u32 v3, v3, v2
	v_mul_hi_u32 v3, v2, v3
	v_add_u32_e32 v2, v2, v3
	v_mul_hi_u32 v2, v1, v2
	v_mul_lo_u32 v3, v2, v0
	v_sub_u32_e32 v1, v1, v3
	v_add_u32_e32 v5, 1, v2
	v_cmp_ge_u32_e32 vcc, v1, v0
	v_sub_u32_e32 v3, v1, v0
	s_nop 0
	v_cndmask_b32_e32 v2, v2, v5, vcc
	v_cndmask_b32_e32 v1, v1, v3, vcc
	v_add_u32_e32 v3, 1, v2
	v_cmp_ge_u32_e32 vcc, v1, v0
	s_nop 1
	v_cndmask_b32_e32 v2, v2, v3, vcc
	v_mul_lo_u32 v1, v0, v2
	v_add_u32_e32 v0, v1, v0
	v_cmp_ne_u32_e32 vcc, v4, v0
	v_mov_b32_e32 v254, v0
	v_mov_b64_e32 v[0:1], s[20:21]
	s_and_saveexec_b64 s[18:19], vcc
	s_cbranch_execz .LBB0_212
	v_mov_b32_e32 v0, 0
	s_sub_u32 s98, s20, 0x100
	s_subb_u32 s99, s21, 0
	global_load_dword v1, v0, s[98:99] sc1
	s_mov_b64 s[26:27], 0
	s_waitcnt vmcnt(0)
	v_cmp_lt_u32_e32 vcc, v1, v254
	s_and_saveexec_b64 s[24:25], vcc
	s_cbranch_execz .LBB0_211
	s_add_u32 s22, s80, 0x60200
	s_addc_u32 s23, s81, 0
	s_mov_b32 s33, 1
	s_branch .LBB0_204

; __device__ __forceinline__ unsigned xb_ld(unsigned* p)              { return __hip_atomic_load(p, __ATOMIC_RELAXED, __HIP_MEMORY_SCOPE_AGENT); }
; #define XB_SPIN(cond, bar) do { unsigned _sp = 0; while (cond) { if (XB_SLEEP) __builtin_amdgcn_s_sleep(1); \
;     if ((++_sp & 255u) == 0u) { if (xb_ld(&(bar)[XB_TMO])) break; if (_sp > XB_SPIN_CAP) { atomicAdd(&(bar)[XB_TMO], 1u); break; } } } } while (0)
; __device__ __forceinline__ void xcd_barrier(const XcdBarrier& b) {
;     ...
;             else XB_SPIN(xb_ld(&bar[XB_TOPGEN]) == tg, bar);
.LBB0_208:
	global_load_dword v1, v0, s[98:99] sc1
	s_add_i32 s33, s33, 1
	s_mov_b64 s[34:35], -1
	s_waitcnt vmcnt(0)
	v_cmp_ge_u32_e32 vcc, v1, v254
	s_orn2_b64 s[38:39], vcc, exec
	s_branch .LBB0_203

; __device__ __forceinline__ unsigned xb_add(unsigned* p, unsigned v) { return __hip_atomic_fetch_add(p, v, __ATOMIC_RELAXED, __HIP_MEMORY_SCOPE_AGENT); }
; __device__ __forceinline__ void xcd_barrier(const XcdBarrier& b) {
;     ...
;             __builtin_amdgcn_fence(__ATOMIC_ACQUIRE, "agent");
;             xb_add(&bar[XB_XGEN(b.x)], 1u);
.LBB0_214:
	s_or_b64 exec, exec, s[18:19]
	s_mov_b64 s[18:19], exec
	v_mbcnt_lo_u32_b32 v0, s18, 0
	v_mbcnt_hi_u32_b32 v0, s19, v0
	v_cmp_eq_u32_e32 vcc, 0, v0
	s_waitcnt vmcnt(0)
	buffer_inv sc1
	s_and_saveexec_b64 s[20:21], vcc
	s_cbranch_execz .LBB0_216
	s_bcnt1_i32_b64 s18, s[18:19]
	v_mov_b32_e32 v0, 0x2000
	v_mov_b32_e32 v1, s18
.LBB0_216:
	s_or_b64 exec, exec, s[20:21]
	s_waitcnt vmcnt(0)

; __device__ __forceinline__ unsigned xb_ld(unsigned* p)              { return __hip_atomic_load(p, __ATOMIC_RELAXED, __HIP_MEMORY_SCOPE_AGENT); }
; __device__ __forceinline__ unsigned xb_add(unsigned* p, unsigned v) { return __hip_atomic_fetch_add(p, v, __ATOMIC_RELAXED, __HIP_MEMORY_SCOPE_AGENT); }
; #define XB_SPIN(cond, bar) do { unsigned _sp = 0; while (cond) { if (XB_SLEEP) __builtin_amdgcn_s_sleep(1); \
;     if ((++_sp & 255u) == 0u) { if (xb_ld(&(bar)[XB_TMO])) break; if (_sp > XB_SPIN_CAP) { atomicAdd(&(bar)[XB_TMO], 1u); break; } } } } while (0)
; __device__ __forceinline__ void xcd_barrier(const XcdBarrier& b) {
;     ...
;         const unsigned old = xb_add(&bar[XB_XSUB(b.x)], 1u);
;         const unsigned gen = old / nloc;
;         if (old + 1u == (gen + 1u) * nloc) {
;             __builtin_amdgcn_fence(__ATOMIC_RELEASE, "agent");
;             asm volatile("s_waitcnt vmcnt(0)" ::: "memory");
;             const unsigned og = xb_add(&bar[XB_TOP], 1u);
;             const unsigned tg = og / nx;
;             if (og + 1u == (tg + 1u) * nx) xb_add(&bar[XB_TOPGEN], 1u);
;             else XB_SPIN(xb_ld(&bar[XB_TOPGEN]) == tg, bar);
;             __builtin_amdgcn_fence(__ATOMIC_ACQUIRE, "agent");
;             xb_add(&bar[XB_XGEN(b.x)], 1u);
;             asm volatile("s_waitcnt vmcnt(0)" ::: "memory");
;         } else {
;             XB_SPIN(xb_ld(&bar[XB_XGEN(b.x)]) == gen, bar);
.LBB0_254:
	s_or_b64 exec, exec, s[18:19]
	v_cvt_f32_u32_e32 v4, v2
	s_waitcnt vmcnt(0)
	v_readfirstlane_b32 s14, v3
	v_sub_u32_e32 v3, 0, v2
	v_rcp_iflag_f32_e32 v4, v4
	v_add_u32_e32 v5, s14, v1
	v_mul_f32_e32 v4, 0x4f7ffffe, v4
	v_cvt_u32_f32_e32 v4, v4
	v_mul_lo_u32 v1, v3, v4
	v_mul_hi_u32 v1, v4, v1
	v_add_u32_e32 v1, v4, v1
	v_mul_hi_u32 v1, v5, v1
	v_mul_lo_u32 v3, v1, v2
	v_sub_u32_e32 v3, v5, v3
	v_add_u32_e32 v4, 1, v1
	v_cmp_ge_u32_e32 vcc, v3, v2
	s_nop 1
	v_cndmask_b32_e32 v1, v1, v4, vcc
	v_sub_u32_e32 v4, v3, v2
	v_cndmask_b32_e32 v3, v3, v4, vcc
	v_add_u32_e32 v4, 1, v1
	v_cmp_ge_u32_e32 vcc, v3, v2
	v_add_u32_e32 v3, 1, v5
	s_nop 0
	v_cndmask_b32_e32 v1, v1, v4, vcc
	v_mul_lo_u32 v4, v2, v1
	v_add_u32_e32 v2, v4, v2
	v_cmp_ne_u32_e32 vcc, v3, v2
	s_and_saveexec_b64 s[14:15], vcc
	s_xor_b64 s[14:15], exec, s[14:15]
	s_cbranch_execz .LBB0_268
	s_waitcnt lgkmcnt(0)
	v_add_u32_e32 v1, 1, v1
	v_mul_lo_u32 v1, v1, v0
	s_add_u32 s22, s86, 0x3400
	s_addc_u32 s23, s87, 0
	v_mov_b32_e32 v0, 0
	global_load_dword v0, v0, s[22:23] sc1
	s_waitcnt vmcnt(0)
	v_cmp_lt_u32_e32 vcc, v0, v1
	s_and_saveexec_b64 s[18:19], vcc
	s_cbranch_execz .LBB0_267
	s_add_u32 s20, s80, 0x60200
	s_addc_u32 s21, s81, 0
	s_mov_b32 s33, 1
	s_mov_b64 s[24:25], 0
	v_mov_b32_e32 v0, 0
	s_branch .LBB0_258

; __device__ __forceinline__ unsigned xb_ld(unsigned* p)              { return __hip_atomic_load(p, __ATOMIC_RELAXED, __HIP_MEMORY_SCOPE_AGENT); }
; #define XB_SPIN(cond, bar) do { unsigned _sp = 0; while (cond) { if (XB_SLEEP) __builtin_amdgcn_s_sleep(1); \
;     if ((++_sp & 255u) == 0u) { if (xb_ld(&(bar)[XB_TMO])) break; if (_sp > XB_SPIN_CAP) { atomicAdd(&(bar)[XB_TMO], 1u); break; } } } } while (0)
; __device__ __forceinline__ void xcd_barrier(const XcdBarrier& b) {
;     ...
;             XB_SPIN(xb_ld(&bar[XB_XGEN(b.x)]) == gen, bar);
.LBB0_262:
	global_load_dword v2, v0, s[22:23] sc1
	s_add_i32 s33, s33, 1
	s_mov_b64 s[34:35], -1
	s_waitcnt vmcnt(0)
	v_cmp_ge_u32_e32 vcc, v2, v1
	s_orn2_b64 s[30:31], vcc, exec
	s_branch .LBB0_257

; __device__ __forceinline__ unsigned xb_ld(unsigned* p)              { return __hip_atomic_load(p, __ATOMIC_RELAXED, __HIP_MEMORY_SCOPE_AGENT); }
; __device__ __forceinline__ unsigned xb_add(unsigned* p, unsigned v) { return __hip_atomic_fetch_add(p, v, __ATOMIC_RELAXED, __HIP_MEMORY_SCOPE_AGENT); }
; #define XB_SPIN(cond, bar) do { unsigned _sp = 0; while (cond) { if (XB_SLEEP) __builtin_amdgcn_s_sleep(1); \
;     if ((++_sp & 255u) == 0u) { if (xb_ld(&(bar)[XB_TMO])) break; if (_sp > XB_SPIN_CAP) { atomicAdd(&(bar)[XB_TMO], 1u); break; } } } } while (0)
; __device__ __forceinline__ void xcd_barrier(const XcdBarrier& b) {
;     ...
;         if (old + 1u == (gen + 1u) * nloc) {
;             __builtin_amdgcn_fence(__ATOMIC_RELEASE, "agent");
;             asm volatile("s_waitcnt vmcnt(0)" ::: "memory");
;             const unsigned og = xb_add(&bar[XB_TOP], 1u);
;             const unsigned tg = og / nx;
;             if (og + 1u == (tg + 1u) * nx) xb_add(&bar[XB_TOPGEN], 1u);
;             else XB_SPIN(xb_ld(&bar[XB_TOPGEN]) == tg, bar);
.LBB0_271:
	s_or_b64 exec, exec, s[18:19]
	v_cvt_f32_u32_e32 v3, v0
	s_waitcnt vmcnt(0)
	v_readfirstlane_b32 s14, v2
	s_add_u32 s18, s80, 0x63500
	s_addc_u32 s19, s81, 0
	v_rcp_iflag_f32_e32 v3, v3
	v_add_u32_e32 v1, s14, v1
	v_add_u32_e32 v4, 1, v1
	s_mov_b64 s[20:21], 0
	v_mul_f32_e32 v2, 0x4f7ffffe, v3
	v_cvt_u32_f32_e32 v2, v2
	v_sub_u32_e32 v3, 0, v0
	v_mul_lo_u32 v3, v3, v2
	v_mul_hi_u32 v3, v2, v3
	v_add_u32_e32 v2, v2, v3
	v_mul_hi_u32 v2, v1, v2
	v_mul_lo_u32 v3, v2, v0
	v_sub_u32_e32 v1, v1, v3
	v_add_u32_e32 v5, 1, v2
	v_cmp_ge_u32_e32 vcc, v1, v0
	v_sub_u32_e32 v3, v1, v0
	s_nop 0
	v_cndmask_b32_e32 v2, v2, v5, vcc
	v_cndmask_b32_e32 v1, v1, v3, vcc
	v_add_u32_e32 v3, 1, v2
	v_cmp_ge_u32_e32 vcc, v1, v0
	s_nop 1
	v_cndmask_b32_e32 v2, v2, v3, vcc
	v_mul_lo_u32 v1, v0, v2
	v_add_u32_e32 v0, v1, v0
	v_cmp_ne_u32_e32 vcc, v4, v0
	v_mov_b32_e32 v254, v0
	v_mov_b64_e32 v[0:1], s[18:19]
	s_and_saveexec_b64 s[14:15], vcc
	s_cbranch_execz .LBB0_283
	v_mov_b32_e32 v0, 0
	s_sub_u32 s98, s18, 0x100
	s_subb_u32 s99, s19, 0
	global_load_dword v1, v0, s[98:99] sc1
	s_mov_b64 s[24:25], 0
	s_waitcnt vmcnt(0)
	v_cmp_lt_u32_e32 vcc, v1, v254
	s_and_saveexec_b64 s[22:23], vcc
	s_cbranch_execz .LBB0_282
	s_add_u32 s20, s80, 0x60200
	s_addc_u32 s21, s81, 0
	s_mov_b32 s33, 1
	s_branch .LBB0_275

; __device__ __forceinline__ unsigned xb_ld(unsigned* p)              { return __hip_atomic_load(p, __ATOMIC_RELAXED, __HIP_MEMORY_SCOPE_AGENT); }
; #define XB_SPIN(cond, bar) do { unsigned _sp = 0; while (cond) { if (XB_SLEEP) __builtin_amdgcn_s_sleep(1); \
;     if ((++_sp & 255u) == 0u) { if (xb_ld(&(bar)[XB_TMO])) break; if (_sp > XB_SPIN_CAP) { atomicAdd(&(bar)[XB_TMO], 1u); break; } } } } while (0)
; __device__ __forceinline__ void xcd_barrier(const XcdBarrier& b) {
;     ...
;             else XB_SPIN(xb_ld(&bar[XB_TOPGEN]) == tg, bar);
.LBB0_279:
	global_load_dword v1, v0, s[98:99] sc1
	s_add_i32 s33, s33, 1
	s_mov_b64 s[30:31], -1
	s_waitcnt vmcnt(0)
	v_cmp_ge_u32_e32 vcc, v1, v254
	s_orn2_b64 s[36:37], vcc, exec
	s_branch .LBB0_274

; __device__ __forceinline__ unsigned xb_add(unsigned* p, unsigned v) { return __hip_atomic_fetch_add(p, v, __ATOMIC_RELAXED, __HIP_MEMORY_SCOPE_AGENT); }
; __device__ __forceinline__ void xcd_barrier(const XcdBarrier& b) {
;     ...
;             __builtin_amdgcn_fence(__ATOMIC_ACQUIRE, "agent");
;             xb_add(&bar[XB_XGEN(b.x)], 1u);
.LBB0_285:
	s_or_b64 exec, exec, s[14:15]
	s_mov_b64 s[14:15], exec
	v_mbcnt_lo_u32_b32 v0, s14, 0
	v_mbcnt_hi_u32_b32 v0, s15, v0
	v_cmp_eq_u32_e32 vcc, 0, v0
	s_waitcnt vmcnt(0)
	buffer_inv sc1
	s_and_saveexec_b64 s[18:19], vcc
	s_cbranch_execz .LBB0_287
	s_bcnt1_i32_b64 s14, s[14:15]
	v_mov_b32_e32 v0, 0x2000
	v_mov_b32_e32 v1, s14
.LBB0_287:
	s_or_b64 exec, exec, s[18:19]
	s_waitcnt vmcnt(0)

; __device__ __forceinline__ unsigned xb_ld(unsigned* p)              { return __hip_atomic_load(p, __ATOMIC_RELAXED, __HIP_MEMORY_SCOPE_AGENT); }
; __device__ __forceinline__ unsigned xb_add(unsigned* p, unsigned v) { return __hip_atomic_fetch_add(p, v, __ATOMIC_RELAXED, __HIP_MEMORY_SCOPE_AGENT); }
; #define XB_SPIN(cond, bar) do { unsigned _sp = 0; while (cond) { if (XB_SLEEP) __builtin_amdgcn_s_sleep(1); \
;     if ((++_sp & 255u) == 0u) { if (xb_ld(&(bar)[XB_TMO])) break; if (_sp > XB_SPIN_CAP) { atomicAdd(&(bar)[XB_TMO], 1u); break; } } } } while (0)
; __device__ __forceinline__ void xcd_barrier(const XcdBarrier& b) {
;     ...
;         const unsigned old = xb_add(&bar[XB_XSUB(b.x)], 1u);
;         const unsigned gen = old / nloc;
;         if (old + 1u == (gen + 1u) * nloc) {
;             __builtin_amdgcn_fence(__ATOMIC_RELEASE, "agent");
;             asm volatile("s_waitcnt vmcnt(0)" ::: "memory");
;             const unsigned og = xb_add(&bar[XB_TOP], 1u);
;             const unsigned tg = og / nx;
;             if (og + 1u == (tg + 1u) * nx) xb_add(&bar[XB_TOPGEN], 1u);
;             else XB_SPIN(xb_ld(&bar[XB_TOPGEN]) == tg, bar);
;             __builtin_amdgcn_fence(__ATOMIC_ACQUIRE, "agent");
;             xb_add(&bar[XB_XGEN(b.x)], 1u);
;             asm volatile("s_waitcnt vmcnt(0)" ::: "memory");
;         } else {
;             XB_SPIN(xb_ld(&bar[XB_XGEN(b.x)]) == gen, bar);
.LBB0_368:
	s_or_b64 exec, exec, s[16:17]
	v_cvt_f32_u32_e32 v4, v2
	s_waitcnt vmcnt(0)
	v_readfirstlane_b32 s14, v3
	v_sub_u32_e32 v3, 0, v2
	v_rcp_iflag_f32_e32 v4, v4
	v_add_u32_e32 v5, s14, v1
	v_mul_f32_e32 v4, 0x4f7ffffe, v4
	v_cvt_u32_f32_e32 v4, v4
	v_mul_lo_u32 v1, v3, v4
	v_mul_hi_u32 v1, v4, v1
	v_add_u32_e32 v1, v4, v1
	v_mul_hi_u32 v1, v5, v1
	v_mul_lo_u32 v3, v1, v2
	v_sub_u32_e32 v3, v5, v3
	v_add_u32_e32 v4, 1, v1
	v_cmp_ge_u32_e32 vcc, v3, v2
	s_nop 1
	v_cndmask_b32_e32 v1, v1, v4, vcc
	v_sub_u32_e32 v4, v3, v2
	v_cndmask_b32_e32 v3, v3, v4, vcc
	v_add_u32_e32 v4, 1, v1
	v_cmp_ge_u32_e32 vcc, v3, v2
	v_add_u32_e32 v3, 1, v5
	s_nop 0
	v_cndmask_b32_e32 v1, v1, v4, vcc
	v_mul_lo_u32 v4, v2, v1
	v_add_u32_e32 v2, v4, v2
	v_cmp_ne_u32_e32 vcc, v3, v2
	s_and_saveexec_b64 s[14:15], vcc
	s_xor_b64 s[14:15], exec, s[14:15]
	s_cbranch_execz .LBB0_382
	s_waitcnt lgkmcnt(0)
	v_add_u32_e32 v1, 1, v1
	v_mul_lo_u32 v1, v1, v0
	s_add_u32 s20, s86, 0x3400
	s_addc_u32 s21, s87, 0
	v_mov_b32_e32 v0, 0
	global_load_dword v0, v0, s[20:21] sc1
	s_waitcnt vmcnt(0)
	v_cmp_lt_u32_e32 vcc, v0, v1
	s_and_saveexec_b64 s[16:17], vcc
	s_cbranch_execz .LBB0_381
	s_add_u32 s18, s80, 0x60200
	s_addc_u32 s19, s81, 0
	s_mov_b32 s33, 1
	s_mov_b64 s[22:23], 0
	v_mov_b32_e32 v0, 0
	s_branch .LBB0_372

; __device__ __forceinline__ unsigned xb_ld(unsigned* p)              { return __hip_atomic_load(p, __ATOMIC_RELAXED, __HIP_MEMORY_SCOPE_AGENT); }
; #define XB_SPIN(cond, bar) do { unsigned _sp = 0; while (cond) { if (XB_SLEEP) __builtin_amdgcn_s_sleep(1); \
;     if ((++_sp & 255u) == 0u) { if (xb_ld(&(bar)[XB_TMO])) break; if (_sp > XB_SPIN_CAP) { atomicAdd(&(bar)[XB_TMO], 1u); break; } } } } while (0)
; __device__ __forceinline__ void xcd_barrier(const XcdBarrier& b) {
;     ...
;             XB_SPIN(xb_ld(&bar[XB_XGEN(b.x)]) == gen, bar);
.LBB0_376:
	global_load_dword v2, v0, s[20:21] sc1
	s_add_i32 s33, s33, 1
	s_mov_b64 s[30:31], -1
	s_waitcnt vmcnt(0)
	v_cmp_ge_u32_e32 vcc, v2, v1
	s_orn2_b64 s[26:27], vcc, exec
	s_branch .LBB0_371

; __device__ __forceinline__ unsigned xb_ld(unsigned* p)              { return __hip_atomic_load(p, __ATOMIC_RELAXED, __HIP_MEMORY_SCOPE_AGENT); }
; __device__ __forceinline__ unsigned xb_add(unsigned* p, unsigned v) { return __hip_atomic_fetch_add(p, v, __ATOMIC_RELAXED, __HIP_MEMORY_SCOPE_AGENT); }
; #define XB_SPIN(cond, bar) do { unsigned _sp = 0; while (cond) { if (XB_SLEEP) __builtin_amdgcn_s_sleep(1); \
;     if ((++_sp & 255u) == 0u) { if (xb_ld(&(bar)[XB_TMO])) break; if (_sp > XB_SPIN_CAP) { atomicAdd(&(bar)[XB_TMO], 1u); break; } } } } while (0)
; __device__ __forceinline__ void xcd_barrier(const XcdBarrier& b) {
;     ...
;         if (old + 1u == (gen + 1u) * nloc) {
;             __builtin_amdgcn_fence(__ATOMIC_RELEASE, "agent");
;             asm volatile("s_waitcnt vmcnt(0)" ::: "memory");
;             const unsigned og = xb_add(&bar[XB_TOP], 1u);
;             const unsigned tg = og / nx;
;             if (og + 1u == (tg + 1u) * nx) xb_add(&bar[XB_TOPGEN], 1u);
;             else XB_SPIN(xb_ld(&bar[XB_TOPGEN]) == tg, bar);
.LBB0_385:
	s_or_b64 exec, exec, s[16:17]
	v_cvt_f32_u32_e32 v3, v0
	s_waitcnt vmcnt(0)
	v_readfirstlane_b32 s14, v2
	s_add_u32 s16, s80, 0x63500
	s_addc_u32 s17, s81, 0
	v_rcp_iflag_f32_e32 v3, v3
	v_add_u32_e32 v1, s14, v1
	v_add_u32_e32 v4, 1, v1
	s_mov_b64 s[18:19], 0
	v_mul_f32_e32 v2, 0x4f7ffffe, v3
	v_cvt_u32_f32_e32 v2, v2
	v_sub_u32_e32 v3, 0, v0
	v_mul_lo_u32 v3, v3, v2
	v_mul_hi_u32 v3, v2, v3
	v_add_u32_e32 v2, v2, v3
	v_mul_hi_u32 v2, v1, v2
	v_mul_lo_u32 v3, v2, v0
	v_sub_u32_e32 v1, v1, v3
	v_add_u32_e32 v5, 1, v2
	v_cmp_ge_u32_e32 vcc, v1, v0
	v_sub_u32_e32 v3, v1, v0
	s_nop 0
	v_cndmask_b32_e32 v2, v2, v5, vcc
	v_cndmask_b32_e32 v1, v1, v3, vcc
	v_add_u32_e32 v3, 1, v2
	v_cmp_ge_u32_e32 vcc, v1, v0
	s_nop 1
	v_cndmask_b32_e32 v2, v2, v3, vcc
	v_mul_lo_u32 v1, v0, v2
	v_add_u32_e32 v0, v1, v0
	v_cmp_ne_u32_e32 vcc, v4, v0
	v_mov_b32_e32 v254, v0
	v_mov_b64_e32 v[0:1], s[16:17]
	s_and_saveexec_b64 s[14:15], vcc
	s_cbranch_execz .LBB0_397
	v_mov_b32_e32 v0, 0
	s_sub_u32 s98, s16, 0x100
	s_subb_u32 s99, s17, 0
	global_load_dword v1, v0, s[98:99] sc1
	s_mov_b64 s[22:23], 0
	s_waitcnt vmcnt(0)
	v_cmp_lt_u32_e32 vcc, v1, v254
	s_and_saveexec_b64 s[20:21], vcc
	s_cbranch_execz .LBB0_396
	s_add_u32 s18, s80, 0x60200
	s_addc_u32 s19, s81, 0
	s_mov_b32 s33, 1
	s_branch .LBB0_389

; __device__ __forceinline__ unsigned xb_ld(unsigned* p)              { return __hip_atomic_load(p, __ATOMIC_RELAXED, __HIP_MEMORY_SCOPE_AGENT); }
; #define XB_SPIN(cond, bar) do { unsigned _sp = 0; while (cond) { if (XB_SLEEP) __builtin_amdgcn_s_sleep(1); \
;     if ((++_sp & 255u) == 0u) { if (xb_ld(&(bar)[XB_TMO])) break; if (_sp > XB_SPIN_CAP) { atomicAdd(&(bar)[XB_TMO], 1u); break; } } } } while (0)
; __device__ __forceinline__ void xcd_barrier(const XcdBarrier& b) {
;     ...
;             else XB_SPIN(xb_ld(&bar[XB_TOPGEN]) == tg, bar);
.LBB0_393:
	global_load_dword v1, v0, s[98:99] sc1
	s_add_i32 s33, s33, 1
	s_mov_b64 s[26:27], -1
	s_waitcnt vmcnt(0)
	v_cmp_ge_u32_e32 vcc, v1, v254
	s_orn2_b64 s[34:35], vcc, exec
	s_branch .LBB0_388

; __device__ __forceinline__ unsigned xb_add(unsigned* p, unsigned v) { return __hip_atomic_fetch_add(p, v, __ATOMIC_RELAXED, __HIP_MEMORY_SCOPE_AGENT); }
; __device__ __forceinline__ void xcd_barrier(const XcdBarrier& b) {
;     ...
;             __builtin_amdgcn_fence(__ATOMIC_ACQUIRE, "agent");
;             xb_add(&bar[XB_XGEN(b.x)], 1u);
.LBB0_399:
	s_or_b64 exec, exec, s[14:15]
	s_mov_b64 s[14:15], exec
	v_mbcnt_lo_u32_b32 v0, s14, 0
	v_mbcnt_hi_u32_b32 v0, s15, v0
	v_cmp_eq_u32_e32 vcc, 0, v0
	s_waitcnt vmcnt(0)
	buffer_inv sc1
	s_and_saveexec_b64 s[16:17], vcc
	s_cbranch_execz .LBB0_401
	s_bcnt1_i32_b64 s14, s[14:15]
	v_mov_b32_e32 v0, 0x2000
	v_mov_b32_e32 v1, s14
.LBB0_401:
	s_or_b64 exec, exec, s[16:17]
	s_waitcnt vmcnt(0)

; __device__ __forceinline__ unsigned xb_ld(unsigned* p)              { return __hip_atomic_load(p, __ATOMIC_RELAXED, __HIP_MEMORY_SCOPE_AGENT); }
; __device__ __forceinline__ unsigned xb_add(unsigned* p, unsigned v) { return __hip_atomic_fetch_add(p, v, __ATOMIC_RELAXED, __HIP_MEMORY_SCOPE_AGENT); }
; #define XB_SPIN(cond, bar) do { unsigned _sp = 0; while (cond) { if (XB_SLEEP) __builtin_amdgcn_s_sleep(1); \
;     if ((++_sp & 255u) == 0u) { if (xb_ld(&(bar)[XB_TMO])) break; if (_sp > XB_SPIN_CAP) { atomicAdd(&(bar)[XB_TMO], 1u); break; } } } } while (0)
; __device__ __forceinline__ void xcd_barrier(const XcdBarrier& b) {
;     ...
;         const unsigned old = xb_add(&bar[XB_XSUB(b.x)], 1u);
;         const unsigned gen = old / nloc;
;         if (old + 1u == (gen + 1u) * nloc) {
;             __builtin_amdgcn_fence(__ATOMIC_RELEASE, "agent");
;             asm volatile("s_waitcnt vmcnt(0)" ::: "memory");
;             const unsigned og = xb_add(&bar[XB_TOP], 1u);
;             const unsigned tg = og / nx;
;             if (og + 1u == (tg + 1u) * nx) xb_add(&bar[XB_TOPGEN], 1u);
;             else XB_SPIN(xb_ld(&bar[XB_TOPGEN]) == tg, bar);
;             __builtin_amdgcn_fence(__ATOMIC_ACQUIRE, "agent");
;             xb_add(&bar[XB_XGEN(b.x)], 1u);
;             asm volatile("s_waitcnt vmcnt(0)" ::: "memory");
;         } else {
;             XB_SPIN(xb_ld(&bar[XB_XGEN(b.x)]) == gen, bar);
.LBB0_474:
	s_or_b64 exec, exec, s[8:9]
	v_cvt_f32_u32_e32 v4, v2
	s_waitcnt vmcnt(0)
	v_readfirstlane_b32 s6, v3
	v_sub_u32_e32 v3, 0, v2
	v_rcp_iflag_f32_e32 v4, v4
	v_add_u32_e32 v5, s6, v1
	v_mul_f32_e32 v4, 0x4f7ffffe, v4
	v_cvt_u32_f32_e32 v4, v4
	v_mul_lo_u32 v1, v3, v4
	v_mul_hi_u32 v1, v4, v1
	v_add_u32_e32 v1, v4, v1
	v_mul_hi_u32 v1, v5, v1
	v_mul_lo_u32 v3, v1, v2
	v_sub_u32_e32 v3, v5, v3
	v_add_u32_e32 v4, 1, v1
	v_cmp_ge_u32_e32 vcc, v3, v2
	s_nop 1
	v_cndmask_b32_e32 v1, v1, v4, vcc
	v_sub_u32_e32 v4, v3, v2
	v_cndmask_b32_e32 v3, v3, v4, vcc
	v_add_u32_e32 v4, 1, v1
	v_cmp_ge_u32_e32 vcc, v3, v2
	v_add_u32_e32 v3, 1, v5
	s_nop 0
	v_cndmask_b32_e32 v1, v1, v4, vcc
	v_mul_lo_u32 v4, v2, v1
	v_add_u32_e32 v2, v4, v2
	v_cmp_ne_u32_e32 vcc, v3, v2
	s_and_saveexec_b64 s[6:7], vcc
	s_xor_b64 s[6:7], exec, s[6:7]
	s_cbranch_execz .LBB0_488
	s_waitcnt lgkmcnt(0)
	v_add_u32_e32 v1, 1, v1
	v_mul_lo_u32 v1, v1, v0
	s_add_u32 s16, s86, 0x3400
	s_addc_u32 s17, s87, 0
	v_mov_b32_e32 v0, 0
	global_load_dword v0, v0, s[16:17] sc1
	s_waitcnt vmcnt(0)
	v_cmp_lt_u32_e32 vcc, v0, v1
	s_and_saveexec_b64 s[8:9], vcc
	s_cbranch_execz .LBB0_487
	s_add_u32 s10, s80, 0x60200
	s_addc_u32 s11, s81, 0
	s_mov_b32 s28, 1
	s_mov_b64 s[18:19], 0
	v_mov_b32_e32 v0, 0
	s_branch .LBB0_478

; __device__ __forceinline__ unsigned xb_ld(unsigned* p)              { return __hip_atomic_load(p, __ATOMIC_RELAXED, __HIP_MEMORY_SCOPE_AGENT); }
; #define XB_SPIN(cond, bar) do { unsigned _sp = 0; while (cond) { if (XB_SLEEP) __builtin_amdgcn_s_sleep(1); \
;     if ((++_sp & 255u) == 0u) { if (xb_ld(&(bar)[XB_TMO])) break; if (_sp > XB_SPIN_CAP) { atomicAdd(&(bar)[XB_TMO], 1u); break; } } } } while (0)
; __device__ __forceinline__ void xcd_barrier(const XcdBarrier& b) {
;     ...
;             XB_SPIN(xb_ld(&bar[XB_XGEN(b.x)]) == gen, bar);
.LBB0_482:
	global_load_dword v2, v0, s[16:17] sc1
	s_add_i32 s28, s28, 1
	s_mov_b64 s[24:25], -1
	s_waitcnt vmcnt(0)
	v_cmp_ge_u32_e32 vcc, v2, v1
	s_orn2_b64 s[22:23], vcc, exec
	s_branch .LBB0_477

; __device__ __forceinline__ unsigned xb_ld(unsigned* p)              { return __hip_atomic_load(p, __ATOMIC_RELAXED, __HIP_MEMORY_SCOPE_AGENT); }
; __device__ __forceinline__ unsigned xb_add(unsigned* p, unsigned v) { return __hip_atomic_fetch_add(p, v, __ATOMIC_RELAXED, __HIP_MEMORY_SCOPE_AGENT); }
; #define XB_SPIN(cond, bar) do { unsigned _sp = 0; while (cond) { if (XB_SLEEP) __builtin_amdgcn_s_sleep(1); \
;     if ((++_sp & 255u) == 0u) { if (xb_ld(&(bar)[XB_TMO])) break; if (_sp > XB_SPIN_CAP) { atomicAdd(&(bar)[XB_TMO], 1u); break; } } } } while (0)
; __device__ __forceinline__ void xcd_barrier(const XcdBarrier& b) {
;     ...
;         if (old + 1u == (gen + 1u) * nloc) {
;             __builtin_amdgcn_fence(__ATOMIC_RELEASE, "agent");
;             asm volatile("s_waitcnt vmcnt(0)" ::: "memory");
;             const unsigned og = xb_add(&bar[XB_TOP], 1u);
;             const unsigned tg = og / nx;
;             if (og + 1u == (tg + 1u) * nx) xb_add(&bar[XB_TOPGEN], 1u);
;             else XB_SPIN(xb_ld(&bar[XB_TOPGEN]) == tg, bar);
.LBB0_491:
	s_or_b64 exec, exec, s[8:9]
	v_cvt_f32_u32_e32 v3, v0
	s_waitcnt vmcnt(0)
	v_readfirstlane_b32 s6, v2
	s_add_u32 s8, s80, 0x63500
	s_addc_u32 s9, s81, 0
	v_rcp_iflag_f32_e32 v3, v3
	v_add_u32_e32 v1, s6, v1
	v_add_u32_e32 v4, 1, v1
	s_mov_b64 s[10:11], 0
	v_mul_f32_e32 v2, 0x4f7ffffe, v3
	v_cvt_u32_f32_e32 v2, v2
	v_sub_u32_e32 v3, 0, v0
	v_mul_lo_u32 v3, v3, v2
	v_mul_hi_u32 v3, v2, v3
	v_add_u32_e32 v2, v2, v3
	v_mul_hi_u32 v2, v1, v2
	v_mul_lo_u32 v3, v2, v0
	v_sub_u32_e32 v1, v1, v3
	v_add_u32_e32 v5, 1, v2
	v_cmp_ge_u32_e32 vcc, v1, v0
	v_sub_u32_e32 v3, v1, v0
	s_nop 0
	v_cndmask_b32_e32 v2, v2, v5, vcc
	v_cndmask_b32_e32 v1, v1, v3, vcc
	v_add_u32_e32 v3, 1, v2
	v_cmp_ge_u32_e32 vcc, v1, v0
	s_nop 1
	v_cndmask_b32_e32 v2, v2, v3, vcc
	v_mul_lo_u32 v1, v0, v2
	v_add_u32_e32 v0, v1, v0
	v_cmp_ne_u32_e32 vcc, v4, v0
	v_mov_b32_e32 v254, v0
	v_mov_b64_e32 v[0:1], s[8:9]
	s_and_saveexec_b64 s[6:7], vcc
	s_cbranch_execz .LBB0_503
	v_mov_b32_e32 v0, 0
	s_sub_u32 s98, s8, 0x100
	s_subb_u32 s99, s9, 0
	global_load_dword v1, v0, s[98:99] sc1
	s_mov_b64 s[18:19], 0
	s_waitcnt vmcnt(0)
	v_cmp_lt_u32_e32 vcc, v1, v254
	s_and_saveexec_b64 s[16:17], vcc
	s_cbranch_execz .LBB0_502
	s_add_u32 s10, s80, 0x60200
	s_addc_u32 s11, s81, 0
	s_mov_b32 s28, 1
	s_branch .LBB0_495

; __device__ __forceinline__ unsigned xb_ld(unsigned* p)              { return __hip_atomic_load(p, __ATOMIC_RELAXED, __HIP_MEMORY_SCOPE_AGENT); }
; #define XB_SPIN(cond, bar) do { unsigned _sp = 0; while (cond) { if (XB_SLEEP) __builtin_amdgcn_s_sleep(1); \
;     if ((++_sp & 255u) == 0u) { if (xb_ld(&(bar)[XB_TMO])) break; if (_sp > XB_SPIN_CAP) { atomicAdd(&(bar)[XB_TMO], 1u); break; } } } } while (0)
; __device__ __forceinline__ void xcd_barrier(const XcdBarrier& b) {
;     ...
;             else XB_SPIN(xb_ld(&bar[XB_TOPGEN]) == tg, bar);
.LBB0_499:
	global_load_dword v1, v0, s[98:99] sc1
	s_add_i32 s28, s28, 1
	s_mov_b64 s[22:23], -1
	s_waitcnt vmcnt(0)
	v_cmp_ge_u32_e32 vcc, v1, v254
	s_orn2_b64 s[26:27], vcc, exec
	s_branch .LBB0_494

; __device__ __forceinline__ unsigned xb_add(unsigned* p, unsigned v) { return __hip_atomic_fetch_add(p, v, __ATOMIC_RELAXED, __HIP_MEMORY_SCOPE_AGENT); }
; __device__ __forceinline__ void xcd_barrier(const XcdBarrier& b) {
;     ...
;             __builtin_amdgcn_fence(__ATOMIC_ACQUIRE, "agent");
;             xb_add(&bar[XB_XGEN(b.x)], 1u);
.LBB0_505:
	s_or_b64 exec, exec, s[6:7]
	s_mov_b64 s[6:7], exec
	v_mbcnt_lo_u32_b32 v0, s6, 0
	v_mbcnt_hi_u32_b32 v0, s7, v0
	v_cmp_eq_u32_e32 vcc, 0, v0
	s_waitcnt vmcnt(0)
	buffer_inv sc1
	s_and_saveexec_b64 s[8:9], vcc
	s_cbranch_execz .LBB0_507
	s_bcnt1_i32_b64 s6, s[6:7]
	v_mov_b32_e32 v0, 0x2000
	v_mov_b32_e32 v1, s6
.LBB0_507:
	s_or_b64 exec, exec, s[8:9]
	s_waitcnt vmcnt(0)

; __device__ __forceinline__ unsigned xb_ld(unsigned* p)              { return __hip_atomic_load(p, __ATOMIC_RELAXED, __HIP_MEMORY_SCOPE_AGENT); }
; __device__ __forceinline__ unsigned xb_add(unsigned* p, unsigned v) { return __hip_atomic_fetch_add(p, v, __ATOMIC_RELAXED, __HIP_MEMORY_SCOPE_AGENT); }
; #define XB_SPIN(cond, bar) do { unsigned _sp = 0; while (cond) { if (XB_SLEEP) __builtin_amdgcn_s_sleep(1); \
;     if ((++_sp & 255u) == 0u) { if (xb_ld(&(bar)[XB_TMO])) break; if (_sp > XB_SPIN_CAP) { atomicAdd(&(bar)[XB_TMO], 1u); break; } } } } while (0)
; __device__ __forceinline__ void xcd_barrier(const XcdBarrier& b) {
;     ...
;             const unsigned og = xb_add(&bar[XB_TOP], 1u);
;             const unsigned tg = og / nx;
;             if (og + 1u == (tg + 1u) * nx) xb_add(&bar[XB_TOPGEN], 1u);
;             else XB_SPIN(xb_ld(&bar[XB_TOPGEN]) == tg, bar);
.LBB0_645:
	s_or_b64 exec, exec, s[8:9]
	v_cvt_f32_u32_e32 v4, v2
	s_waitcnt vmcnt(0)
	v_readfirstlane_b32 s6, v3
	v_sub_u32_e32 v3, 0, v2
	v_rcp_iflag_f32_e32 v4, v4
	v_add_u32_e32 v5, s6, v1
	v_mul_f32_e32 v4, 0x4f7ffffe, v4
	v_cvt_u32_f32_e32 v4, v4
	v_mul_lo_u32 v1, v3, v4
	v_mul_hi_u32 v1, v4, v1
	v_add_u32_e32 v1, v4, v1
	v_mul_hi_u32 v1, v5, v1
	v_mul_lo_u32 v3, v1, v2
	v_sub_u32_e32 v3, v5, v3
	v_add_u32_e32 v4, 1, v1
	v_cmp_ge_u32_e32 vcc, v3, v2
	s_nop 1
	v_cndmask_b32_e32 v1, v1, v4, vcc
	v_sub_u32_e32 v4, v3, v2
	v_cndmask_b32_e32 v3, v3, v4, vcc
	v_add_u32_e32 v4, 1, v1
	v_cmp_ge_u32_e32 vcc, v3, v2
	v_add_u32_e32 v3, 1, v5
	s_nop 0
	v_cndmask_b32_e32 v1, v1, v4, vcc
	v_mul_lo_u32 v4, v2, v1
	v_add_u32_e32 v2, v4, v2
	v_cmp_ne_u32_e32 vcc, v3, v2
	s_and_saveexec_b64 s[6:7], vcc
	s_xor_b64 s[6:7], exec, s[6:7]
	s_cbranch_execz .LBB0_659
	s_waitcnt lgkmcnt(0)
	v_add_u32_e32 v1, 1, v1
	v_mul_lo_u32 v1, v1, v0
	s_add_u32 s14, s86, 0x3400
	s_addc_u32 s15, s87, 0
	v_mov_b32_e32 v0, 0
	global_load_dword v0, v0, s[14:15] sc1
	s_waitcnt vmcnt(0)
	v_cmp_lt_u32_e32 vcc, v0, v1
	s_and_saveexec_b64 s[8:9], vcc
	s_cbranch_execz .LBB0_658
	s_add_u32 s10, s80, 0x60200
	s_addc_u32 s11, s81, 0
	s_mov_b32 s26, 1
	s_mov_b64 s[16:17], 0
	v_mov_b32_e32 v0, 0
	s_branch .LBB0_649

; __device__ __forceinline__ unsigned xb_ld(unsigned* p)              { return __hip_atomic_load(p, __ATOMIC_RELAXED, __HIP_MEMORY_SCOPE_AGENT); }
; #define XB_SPIN(cond, bar) do { unsigned _sp = 0; while (cond) { if (XB_SLEEP) __builtin_amdgcn_s_sleep(1); \
;     if ((++_sp & 255u) == 0u) { if (xb_ld(&(bar)[XB_TMO])) break; if (_sp > XB_SPIN_CAP) { atomicAdd(&(bar)[XB_TMO], 1u); break; } } } } while (0)
; __device__ __forceinline__ void xcd_barrier(const XcdBarrier& b) {
;     ...
;             else XB_SPIN(xb_ld(&bar[XB_TOPGEN]) == tg, bar);
.LBB0_653:
	global_load_dword v2, v0, s[14:15] sc1
	s_add_i32 s26, s26, 1
	s_mov_b64 s[22:23], -1
	s_waitcnt vmcnt(0)
	v_cmp_ge_u32_e32 vcc, v2, v1
	s_orn2_b64 s[20:21], vcc, exec
	s_branch .LBB0_648

; __device__ __forceinline__ unsigned xb_ld(unsigned* p)              { return __hip_atomic_load(p, __ATOMIC_RELAXED, __HIP_MEMORY_SCOPE_AGENT); }
; __device__ __forceinline__ unsigned xb_add(unsigned* p, unsigned v) { return __hip_atomic_fetch_add(p, v, __ATOMIC_RELAXED, __HIP_MEMORY_SCOPE_AGENT); }
; #define XB_SPIN(cond, bar) do { unsigned _sp = 0; while (cond) { if (XB_SLEEP) __builtin_amdgcn_s_sleep(1); \
;     if ((++_sp & 255u) == 0u) { if (xb_ld(&(bar)[XB_TMO])) break; if (_sp > XB_SPIN_CAP) { atomicAdd(&(bar)[XB_TMO], 1u); break; } } } } while (0)
; __device__ __forceinline__ void xcd_barrier(const XcdBarrier& b) {
;     ...
;             const unsigned og = xb_add(&bar[XB_TOP], 1u);
;             const unsigned tg = og / nx;
;             if (og + 1u == (tg + 1u) * nx) xb_add(&bar[XB_TOPGEN], 1u);
;             else XB_SPIN(xb_ld(&bar[XB_TOPGEN]) == tg, bar);
.LBB0_662:
	s_or_b64 exec, exec, s[8:9]
	v_cvt_f32_u32_e32 v3, v0
	s_waitcnt vmcnt(0)
	v_readfirstlane_b32 s6, v2
	s_add_u32 s8, s80, 0x63500
	s_addc_u32 s9, s81, 0
	v_rcp_iflag_f32_e32 v3, v3
	v_add_u32_e32 v1, s6, v1
	v_add_u32_e32 v4, 1, v1
	s_mov_b64 s[10:11], 0
	v_mul_f32_e32 v2, 0x4f7ffffe, v3
	v_cvt_u32_f32_e32 v2, v2
	v_sub_u32_e32 v3, 0, v0
	v_mul_lo_u32 v3, v3, v2
	v_mul_hi_u32 v3, v2, v3
	v_add_u32_e32 v2, v2, v3
	v_mul_hi_u32 v2, v1, v2
	v_mul_lo_u32 v3, v2, v0
	v_sub_u32_e32 v1, v1, v3
	v_add_u32_e32 v5, 1, v2
	v_cmp_ge_u32_e32 vcc, v1, v0
	v_sub_u32_e32 v3, v1, v0
	s_nop 0
	v_cndmask_b32_e32 v2, v2, v5, vcc
	v_cndmask_b32_e32 v1, v1, v3, vcc
	v_add_u32_e32 v3, 1, v2
	v_cmp_ge_u32_e32 vcc, v1, v0
	s_nop 1
	v_cndmask_b32_e32 v2, v2, v3, vcc
	v_mul_lo_u32 v1, v0, v2
	v_add_u32_e32 v0, v1, v0
	v_cmp_ne_u32_e32 vcc, v4, v0
	v_mov_b32_e32 v254, v0
	v_mov_b64_e32 v[0:1], s[8:9]
	s_and_saveexec_b64 s[6:7], vcc
	s_cbranch_execz .LBB0_674
	v_mov_b32_e32 v0, 0
	s_sub_u32 s98, s8, 0x100
	s_subb_u32 s99, s9, 0
	global_load_dword v1, v0, s[98:99] sc1
	s_mov_b64 s[16:17], 0
	s_waitcnt vmcnt(0)
	v_cmp_lt_u32_e32 vcc, v1, v254
	s_and_saveexec_b64 s[14:15], vcc
	s_cbranch_execz .LBB0_673
	s_add_u32 s10, s80, 0x60200
	s_addc_u32 s11, s81, 0
	s_mov_b32 s26, 1
	s_branch .LBB0_666

; __device__ __forceinline__ unsigned xb_ld(unsigned* p)              { return __hip_atomic_load(p, __ATOMIC_RELAXED, __HIP_MEMORY_SCOPE_AGENT); }
; #define XB_SPIN(cond, bar) do { unsigned _sp = 0; while (cond) { if (XB_SLEEP) __builtin_amdgcn_s_sleep(1); \
;     if ((++_sp & 255u) == 0u) { if (xb_ld(&(bar)[XB_TMO])) break; if (_sp > XB_SPIN_CAP) { atomicAdd(&(bar)[XB_TMO], 1u); break; } } } } while (0)
; __device__ __forceinline__ void xcd_barrier(const XcdBarrier& b) {
;     ...
;             else XB_SPIN(xb_ld(&bar[XB_TOPGEN]) == tg, bar);
.LBB0_670:
	global_load_dword v1, v0, s[98:99] sc1
	s_add_i32 s26, s26, 1
	s_mov_b64 s[20:21], -1
	s_waitcnt vmcnt(0)
	v_cmp_ge_u32_e32 vcc, v1, v254
	s_orn2_b64 s[24:25], vcc, exec
	s_branch .LBB0_665

; __device__ __forceinline__ unsigned xb_add(unsigned* p, unsigned v) { return __hip_atomic_fetch_add(p, v, __ATOMIC_RELAXED, __HIP_MEMORY_SCOPE_AGENT); }
; __device__ __forceinline__ void xcd_barrier(const XcdBarrier& b) {
;     ...
;             __builtin_amdgcn_fence(__ATOMIC_ACQUIRE, "agent");
;             xb_add(&bar[XB_XGEN(b.x)], 1u);
;             asm volatile("s_waitcnt vmcnt(0)" ::: "memory");
.LBB0_676:
	s_or_b64 exec, exec, s[6:7]
	s_mov_b64 s[6:7], exec
	v_mbcnt_lo_u32_b32 v0, s6, 0
	v_mbcnt_hi_u32_b32 v0, s7, v0
	v_cmp_eq_u32_e32 vcc, 0, v0
	s_waitcnt vmcnt(0)
	buffer_inv sc1
	s_and_saveexec_b64 s[8:9], vcc
	s_cbranch_execz .LBB0_678
	s_bcnt1_i32_b64 s6, s[6:7]
	v_mov_b32_e32 v0, 0x2000
	v_mov_b32_e32 v1, s6
.LBB0_678:
	s_or_b64 exec, exec, s[8:9]
	s_waitcnt vmcnt(0)

; __device__ __forceinline__ unsigned xb_ld(unsigned* p)              { return __hip_atomic_load(p, __ATOMIC_RELAXED, __HIP_MEMORY_SCOPE_AGENT); }
; __device__ __forceinline__ unsigned xb_add(unsigned* p, unsigned v) { return __hip_atomic_fetch_add(p, v, __ATOMIC_RELAXED, __HIP_MEMORY_SCOPE_AGENT); }
; #define XB_SPIN(cond, bar) do { unsigned _sp = 0; while (cond) { if (XB_SLEEP) __builtin_amdgcn_s_sleep(1); \
;     if ((++_sp & 255u) == 0u) { if (xb_ld(&(bar)[XB_TMO])) break; if (_sp > XB_SPIN_CAP) { atomicAdd(&(bar)[XB_TMO], 1u); break; } } } } while (0)
; __device__ __forceinline__ void xcd_barrier(const XcdBarrier& b) {
;     ...
;             const unsigned og = xb_add(&bar[XB_TOP], 1u);
;             const unsigned tg = og / nx;
;             if (og + 1u == (tg + 1u) * nx) xb_add(&bar[XB_TOPGEN], 1u);
;             else XB_SPIN(xb_ld(&bar[XB_TOPGEN]) == tg, bar);
.LBB0_830:
	s_or_b64 exec, exec, s[6:7]
	v_cvt_f32_u32_e32 v4, v2
	s_waitcnt vmcnt(0)
	v_readfirstlane_b32 s4, v3
	v_sub_u32_e32 v3, 0, v2
	v_rcp_iflag_f32_e32 v4, v4
	v_add_u32_e32 v5, s4, v1
	v_mul_f32_e32 v4, 0x4f7ffffe, v4
	v_cvt_u32_f32_e32 v4, v4
	v_mul_lo_u32 v1, v3, v4
	v_mul_hi_u32 v1, v4, v1
	v_add_u32_e32 v1, v4, v1
	v_mul_hi_u32 v1, v5, v1
	v_mul_lo_u32 v3, v1, v2
	v_sub_u32_e32 v3, v5, v3
	v_add_u32_e32 v4, 1, v1
	v_cmp_ge_u32_e32 vcc, v3, v2
	s_nop 1
	v_cndmask_b32_e32 v1, v1, v4, vcc
	v_sub_u32_e32 v4, v3, v2
	v_cndmask_b32_e32 v3, v3, v4, vcc
	v_add_u32_e32 v4, 1, v1
	v_cmp_ge_u32_e32 vcc, v3, v2
	v_add_u32_e32 v3, 1, v5
	s_nop 0
	v_cndmask_b32_e32 v1, v1, v4, vcc
	v_mul_lo_u32 v4, v2, v1
	v_add_u32_e32 v2, v4, v2
	v_cmp_ne_u32_e32 vcc, v3, v2
	s_and_saveexec_b64 s[4:5], vcc
	s_xor_b64 s[4:5], exec, s[4:5]
	s_cbranch_execz .LBB0_844
	s_waitcnt lgkmcnt(0)
	v_add_u32_e32 v1, 1, v1
	v_mul_lo_u32 v1, v1, v0
	s_add_u32 s10, s80, 0x3400
	s_addc_u32 s11, s81, 0
	v_mov_b32_e32 v0, 0
	global_load_dword v0, v0, s[10:11] sc1
	s_waitcnt vmcnt(0)
	v_cmp_lt_u32_e32 vcc, v0, v1
	s_and_saveexec_b64 s[6:7], vcc
	s_cbranch_execz .LBB0_843
	s_add_u32 s8, s76, 0x60200
	s_addc_u32 s9, s77, 0
	s_mov_b32 s22, 1
	s_mov_b64 s[12:13], 0
	v_mov_b32_e32 v0, 0
	s_branch .LBB0_834

; __device__ __forceinline__ unsigned xb_ld(unsigned* p)              { return __hip_atomic_load(p, __ATOMIC_RELAXED, __HIP_MEMORY_SCOPE_AGENT); }
; #define XB_SPIN(cond, bar) do { unsigned _sp = 0; while (cond) { if (XB_SLEEP) __builtin_amdgcn_s_sleep(1); \
;     if ((++_sp & 255u) == 0u) { if (xb_ld(&(bar)[XB_TMO])) break; if (_sp > XB_SPIN_CAP) { atomicAdd(&(bar)[XB_TMO], 1u); break; } } } } while (0)
; __device__ __forceinline__ void xcd_barrier(const XcdBarrier& b) {
;     ...
;             else XB_SPIN(xb_ld(&bar[XB_TOPGEN]) == tg, bar);
.LBB0_838:
	global_load_dword v2, v0, s[10:11] sc1
	s_add_i32 s22, s22, 1
	s_mov_b64 s[18:19], -1
	s_waitcnt vmcnt(0)
	v_cmp_ge_u32_e32 vcc, v2, v1
	s_orn2_b64 s[16:17], vcc, exec
	s_branch .LBB0_833

; __device__ __forceinline__ unsigned xb_ld(unsigned* p)              { return __hip_atomic_load(p, __ATOMIC_RELAXED, __HIP_MEMORY_SCOPE_AGENT); }
; __device__ __forceinline__ unsigned xb_add(unsigned* p, unsigned v) { return __hip_atomic_fetch_add(p, v, __ATOMIC_RELAXED, __HIP_MEMORY_SCOPE_AGENT); }
; #define XB_SPIN(cond, bar) do { unsigned _sp = 0; while (cond) { if (XB_SLEEP) __builtin_amdgcn_s_sleep(1); \
;     if ((++_sp & 255u) == 0u) { if (xb_ld(&(bar)[XB_TMO])) break; if (_sp > XB_SPIN_CAP) { atomicAdd(&(bar)[XB_TMO], 1u); break; } } } } while (0)
; __device__ __forceinline__ void xcd_barrier(const XcdBarrier& b) {
;     ...
;             const unsigned og = xb_add(&bar[XB_TOP], 1u);
;             const unsigned tg = og / nx;
;             if (og + 1u == (tg + 1u) * nx) xb_add(&bar[XB_TOPGEN], 1u);
;             else XB_SPIN(xb_ld(&bar[XB_TOPGEN]) == tg, bar);
.LBB0_847:
	s_or_b64 exec, exec, s[6:7]
	v_cvt_f32_u32_e32 v3, v0
	s_waitcnt vmcnt(0)
	v_readfirstlane_b32 s4, v2
	s_add_u32 s6, s76, 0x63500
	s_addc_u32 s7, s77, 0
	v_rcp_iflag_f32_e32 v3, v3
	v_add_u32_e32 v1, s4, v1
	v_add_u32_e32 v4, 1, v1
	s_mov_b64 s[8:9], 0
	v_mul_f32_e32 v2, 0x4f7ffffe, v3
	v_cvt_u32_f32_e32 v2, v2
	v_sub_u32_e32 v3, 0, v0
	v_mul_lo_u32 v3, v3, v2
	v_mul_hi_u32 v3, v2, v3
	v_add_u32_e32 v2, v2, v3
	v_mul_hi_u32 v2, v1, v2
	v_mul_lo_u32 v3, v2, v0
	v_sub_u32_e32 v1, v1, v3
	v_add_u32_e32 v5, 1, v2
	v_cmp_ge_u32_e32 vcc, v1, v0
	v_sub_u32_e32 v3, v1, v0
	s_nop 0
	v_cndmask_b32_e32 v2, v2, v5, vcc
	v_cndmask_b32_e32 v1, v1, v3, vcc
	v_add_u32_e32 v3, 1, v2
	v_cmp_ge_u32_e32 vcc, v1, v0
	s_nop 1
	v_cndmask_b32_e32 v2, v2, v3, vcc
	v_mul_lo_u32 v1, v0, v2
	v_add_u32_e32 v0, v1, v0
	v_cmp_ne_u32_e32 vcc, v4, v0
	v_mov_b32_e32 v254, v0
	v_mov_b64_e32 v[0:1], s[6:7]
	s_and_saveexec_b64 s[4:5], vcc
	s_cbranch_execz .LBB0_859
	v_mov_b32_e32 v0, 0
	s_sub_u32 s98, s6, 0x100
	s_subb_u32 s99, s7, 0
	global_load_dword v1, v0, s[98:99] sc1
	s_mov_b64 s[12:13], 0
	s_waitcnt vmcnt(0)
	v_cmp_lt_u32_e32 vcc, v1, v254
	s_and_saveexec_b64 s[10:11], vcc
	s_cbranch_execz .LBB0_858
	s_add_u32 s8, s76, 0x60200
	s_addc_u32 s9, s77, 0
	s_mov_b32 s22, 1
	s_branch .LBB0_851

; __device__ __forceinline__ unsigned xb_ld(unsigned* p)              { return __hip_atomic_load(p, __ATOMIC_RELAXED, __HIP_MEMORY_SCOPE_AGENT); }
; #define XB_SPIN(cond, bar) do { unsigned _sp = 0; while (cond) { if (XB_SLEEP) __builtin_amdgcn_s_sleep(1); \
;     if ((++_sp & 255u) == 0u) { if (xb_ld(&(bar)[XB_TMO])) break; if (_sp > XB_SPIN_CAP) { atomicAdd(&(bar)[XB_TMO], 1u); break; } } } } while (0)
; __device__ __forceinline__ void xcd_barrier(const XcdBarrier& b) {
;     ...
;             else XB_SPIN(xb_ld(&bar[XB_TOPGEN]) == tg, bar);
.LBB0_855:
	global_load_dword v1, v0, s[98:99] sc1
	s_add_i32 s22, s22, 1
	s_mov_b64 s[16:17], -1
	s_waitcnt vmcnt(0)
	v_cmp_ge_u32_e32 vcc, v1, v254
	s_orn2_b64 s[20:21], vcc, exec
	s_branch .LBB0_850

; __device__ __forceinline__ unsigned xb_add(unsigned* p, unsigned v) { return __hip_atomic_fetch_add(p, v, __ATOMIC_RELAXED, __HIP_MEMORY_SCOPE_AGENT); }
; __device__ __forceinline__ void xcd_barrier(const XcdBarrier& b) {
;     ...
;             __builtin_amdgcn_fence(__ATOMIC_ACQUIRE, "agent");
;             xb_add(&bar[XB_XGEN(b.x)], 1u);
;             asm volatile("s_waitcnt vmcnt(0)" ::: "memory");
.LBB0_861:
	s_or_b64 exec, exec, s[4:5]
	s_mov_b64 s[4:5], exec
	v_mbcnt_lo_u32_b32 v0, s4, 0
	v_mbcnt_hi_u32_b32 v0, s5, v0
	v_cmp_eq_u32_e32 vcc, 0, v0
	s_waitcnt vmcnt(0)
	buffer_inv sc1
	s_and_saveexec_b64 s[6:7], vcc
	s_cbranch_execz .LBB0_863
	s_bcnt1_i32_b64 s4, s[4:5]
	v_mov_b32_e32 v0, 0x2000
	v_mov_b32_e32 v1, s4
.LBB0_863:
	s_or_b64 exec, exec, s[6:7]
	s_waitcnt vmcnt(0)

; __device__ __forceinline__ unsigned xb_add(unsigned* p, unsigned v) { return __hip_atomic_fetch_add(p, v, __ATOMIC_RELAXED, __HIP_MEMORY_SCOPE_AGENT); }
; __device__ __forceinline__ void xcd_barrier(const XcdBarrier& b) {
;     ...
;             __builtin_amdgcn_fence(__ATOMIC_ACQUIRE, "agent");
;             xb_add(&bar[XB_XGEN(b.x)], 1u);
;             asm volatile("s_waitcnt vmcnt(0)" ::: "memory");
.LBB0_957:
	s_or_b64 exec, exec, s[4:5]
	s_mov_b64 s[4:5], exec
	v_mbcnt_lo_u32_b32 v0, s4, 0
	v_mbcnt_hi_u32_b32 v0, s5, v0
	v_cmp_eq_u32_e32 vcc, 0, v0
	s_waitcnt vmcnt(0)
	buffer_inv sc1
	s_and_saveexec_b64 s[6:7], vcc
	s_cbranch_execz .LBB0_959
	s_bcnt1_i32_b64 s4, s[4:5]
	v_mov_b32_e32 v0, 0x2000
	v_mov_b32_e32 v1, s4
.LBB0_959:
	s_or_b64 exec, exec, s[6:7]
	s_waitcnt vmcnt(0)

; __device__ __forceinline__ unsigned xb_ld(unsigned* p)              { return __hip_atomic_load(p, __ATOMIC_RELAXED, __HIP_MEMORY_SCOPE_AGENT); }
; __device__ __forceinline__ unsigned xb_add(unsigned* p, unsigned v) { return __hip_atomic_fetch_add(p, v, __ATOMIC_RELAXED, __HIP_MEMORY_SCOPE_AGENT); }
; #define XB_SPIN(cond, bar) do { unsigned _sp = 0; while (cond) { if (XB_SLEEP) __builtin_amdgcn_s_sleep(1); \
;     if ((++_sp & 255u) == 0u) { if (xb_ld(&(bar)[XB_TMO])) break; if (_sp > XB_SPIN_CAP) { atomicAdd(&(bar)[XB_TMO], 1u); break; } } } } while (0)
; __device__ __forceinline__ void xcd_barrier(const XcdBarrier& b) {
;     ...
;             const unsigned og = xb_add(&bar[XB_TOP], 1u);
;             const unsigned tg = og / nx;
;             if (og + 1u == (tg + 1u) * nx) xb_add(&bar[XB_TOPGEN], 1u);
;             else XB_SPIN(xb_ld(&bar[XB_TOPGEN]) == tg, bar);
.LBB0_995:
	s_or_b64 exec, exec, s[8:9]
	v_cvt_f32_u32_e32 v4, v2
	s_waitcnt vmcnt(0)
	v_readfirstlane_b32 s6, v3
	v_sub_u32_e32 v3, 0, v2
	v_rcp_iflag_f32_e32 v4, v4
	v_add_u32_e32 v5, s6, v1
	v_mul_f32_e32 v4, 0x4f7ffffe, v4
	v_cvt_u32_f32_e32 v4, v4
	v_mul_lo_u32 v1, v3, v4
	v_mul_hi_u32 v1, v4, v1
	v_add_u32_e32 v1, v4, v1
	v_mul_hi_u32 v1, v5, v1
	v_mul_lo_u32 v3, v1, v2
	v_sub_u32_e32 v3, v5, v3
	v_add_u32_e32 v4, 1, v1
	v_cmp_ge_u32_e32 vcc, v3, v2
	s_nop 1
	v_cndmask_b32_e32 v1, v1, v4, vcc
	v_sub_u32_e32 v4, v3, v2
	v_cndmask_b32_e32 v3, v3, v4, vcc
	v_add_u32_e32 v4, 1, v1
	v_cmp_ge_u32_e32 vcc, v3, v2
	v_add_u32_e32 v3, 1, v5
	s_nop 0
	v_cndmask_b32_e32 v1, v1, v4, vcc
	v_mul_lo_u32 v4, v2, v1
	v_add_u32_e32 v2, v4, v2
	v_cmp_ne_u32_e32 vcc, v3, v2
	s_and_saveexec_b64 s[6:7], vcc
	s_xor_b64 s[6:7], exec, s[6:7]
	s_cbranch_execz .LBB0_1009
	s_waitcnt lgkmcnt(0)
	v_add_u32_e32 v1, 1, v1
	v_mul_lo_u32 v1, v1, v0
	s_add_u32 s12, s80, 0x3400
	s_addc_u32 s13, s81, 0
	v_mov_b32_e32 v0, 0
	global_load_dword v0, v0, s[12:13] sc1
	s_waitcnt vmcnt(0)
	v_cmp_lt_u32_e32 vcc, v0, v1
	s_and_saveexec_b64 s[8:9], vcc
	s_cbranch_execz .LBB0_1008
	s_add_u32 s10, s76, 0x60200
	s_addc_u32 s11, s77, 0
	s_mov_b32 s24, 1
	s_mov_b64 s[14:15], 0
	v_mov_b32_e32 v0, 0
	s_branch .LBB0_999

; __device__ __forceinline__ unsigned xb_ld(unsigned* p)              { return __hip_atomic_load(p, __ATOMIC_RELAXED, __HIP_MEMORY_SCOPE_AGENT); }
; #define XB_SPIN(cond, bar) do { unsigned _sp = 0; while (cond) { if (XB_SLEEP) __builtin_amdgcn_s_sleep(1); \
;     if ((++_sp & 255u) == 0u) { if (xb_ld(&(bar)[XB_TMO])) break; if (_sp > XB_SPIN_CAP) { atomicAdd(&(bar)[XB_TMO], 1u); break; } } } } while (0)
; __device__ __forceinline__ void xcd_barrier(const XcdBarrier& b) {
;     ...
;             else XB_SPIN(xb_ld(&bar[XB_TOPGEN]) == tg, bar);
.LBB0_1003:
	global_load_dword v2, v0, s[12:13] sc1
	s_add_i32 s24, s24, 1
	s_mov_b64 s[20:21], -1
	s_waitcnt vmcnt(0)
	v_cmp_ge_u32_e32 vcc, v2, v1
	s_orn2_b64 s[18:19], vcc, exec
	s_branch .LBB0_998

; __device__ __forceinline__ unsigned xb_ld(unsigned* p)              { return __hip_atomic_load(p, __ATOMIC_RELAXED, __HIP_MEMORY_SCOPE_AGENT); }
; __device__ __forceinline__ unsigned xb_add(unsigned* p, unsigned v) { return __hip_atomic_fetch_add(p, v, __ATOMIC_RELAXED, __HIP_MEMORY_SCOPE_AGENT); }
; #define XB_SPIN(cond, bar) do { unsigned _sp = 0; while (cond) { if (XB_SLEEP) __builtin_amdgcn_s_sleep(1); \
;     if ((++_sp & 255u) == 0u) { if (xb_ld(&(bar)[XB_TMO])) break; if (_sp > XB_SPIN_CAP) { atomicAdd(&(bar)[XB_TMO], 1u); break; } } } } while (0)
; __device__ __forceinline__ void xcd_barrier(const XcdBarrier& b) {
;     ...
;             const unsigned og = xb_add(&bar[XB_TOP], 1u);
;             const unsigned tg = og / nx;
;             if (og + 1u == (tg + 1u) * nx) xb_add(&bar[XB_TOPGEN], 1u);
;             else XB_SPIN(xb_ld(&bar[XB_TOPGEN]) == tg, bar);
.LBB0_1012:
	s_or_b64 exec, exec, s[8:9]
	v_cvt_f32_u32_e32 v3, v0
	s_waitcnt vmcnt(0)
	v_readfirstlane_b32 s6, v2
	s_add_u32 s8, s76, 0x63500
	s_addc_u32 s9, s77, 0
	v_rcp_iflag_f32_e32 v3, v3
	v_add_u32_e32 v1, s6, v1
	v_add_u32_e32 v4, 1, v1
	s_mov_b64 s[10:11], 0
	v_mul_f32_e32 v2, 0x4f7ffffe, v3
	v_cvt_u32_f32_e32 v2, v2
	v_sub_u32_e32 v3, 0, v0
	v_mul_lo_u32 v3, v3, v2
	v_mul_hi_u32 v3, v2, v3
	v_add_u32_e32 v2, v2, v3
	v_mul_hi_u32 v2, v1, v2
	v_mul_lo_u32 v3, v2, v0
	v_sub_u32_e32 v1, v1, v3
	v_add_u32_e32 v5, 1, v2
	v_cmp_ge_u32_e32 vcc, v1, v0
	v_sub_u32_e32 v3, v1, v0
	s_nop 0
	v_cndmask_b32_e32 v2, v2, v5, vcc
	v_cndmask_b32_e32 v1, v1, v3, vcc
	v_add_u32_e32 v3, 1, v2
	v_cmp_ge_u32_e32 vcc, v1, v0
	s_nop 1
	v_cndmask_b32_e32 v2, v2, v3, vcc
	v_mul_lo_u32 v1, v0, v2
	v_add_u32_e32 v0, v1, v0
	v_cmp_ne_u32_e32 vcc, v4, v0
	v_mov_b32_e32 v254, v0
	v_mov_b64_e32 v[0:1], s[8:9]
	s_and_saveexec_b64 s[6:7], vcc
	s_cbranch_execz .LBB0_1024
	v_mov_b32_e32 v0, 0
	s_sub_u32 s98, s8, 0x100
	s_subb_u32 s99, s9, 0
	global_load_dword v1, v0, s[98:99] sc1
	s_mov_b64 s[14:15], 0
	s_waitcnt vmcnt(0)
	v_cmp_lt_u32_e32 vcc, v1, v254
	s_and_saveexec_b64 s[12:13], vcc
	s_cbranch_execz .LBB0_1023
	s_add_u32 s10, s76, 0x60200
	s_addc_u32 s11, s77, 0
	s_mov_b32 s24, 1
	s_branch .LBB0_1016

; __device__ __forceinline__ unsigned xb_ld(unsigned* p)              { return __hip_atomic_load(p, __ATOMIC_RELAXED, __HIP_MEMORY_SCOPE_AGENT); }
; #define XB_SPIN(cond, bar) do { unsigned _sp = 0; while (cond) { if (XB_SLEEP) __builtin_amdgcn_s_sleep(1); \
;     if ((++_sp & 255u) == 0u) { if (xb_ld(&(bar)[XB_TMO])) break; if (_sp > XB_SPIN_CAP) { atomicAdd(&(bar)[XB_TMO], 1u); break; } } } } while (0)
; __device__ __forceinline__ void xcd_barrier(const XcdBarrier& b) {
;     ...
;             else XB_SPIN(xb_ld(&bar[XB_TOPGEN]) == tg, bar);
.LBB0_1020:
	global_load_dword v1, v0, s[98:99] sc1
	s_add_i32 s24, s24, 1
	s_mov_b64 s[18:19], -1
	s_waitcnt vmcnt(0)
	v_cmp_ge_u32_e32 vcc, v1, v254
	s_orn2_b64 s[22:23], vcc, exec
	s_branch .LBB0_1015

; __device__ __forceinline__ unsigned xb_add(unsigned* p, unsigned v) { return __hip_atomic_fetch_add(p, v, __ATOMIC_RELAXED, __HIP_MEMORY_SCOPE_AGENT); }
; __device__ __forceinline__ void xcd_barrier(const XcdBarrier& b) {
;     ...
;             __builtin_amdgcn_fence(__ATOMIC_ACQUIRE, "agent");
;             xb_add(&bar[XB_XGEN(b.x)], 1u);
;             asm volatile("s_waitcnt vmcnt(0)" ::: "memory");
.LBB0_1026:
	s_or_b64 exec, exec, s[6:7]
	s_mov_b64 s[6:7], exec
	v_mbcnt_lo_u32_b32 v0, s6, 0
	v_mbcnt_hi_u32_b32 v0, s7, v0
	v_cmp_eq_u32_e32 vcc, 0, v0
	s_waitcnt vmcnt(0)
	buffer_inv sc1
	s_and_saveexec_b64 s[8:9], vcc
	s_cbranch_execz .LBB0_1028
	s_bcnt1_i32_b64 s6, s[6:7]
	v_mov_b32_e32 v0, 0x2000
	v_mov_b32_e32 v1, s6
.LBB0_1028:
	s_or_b64 exec, exec, s[8:9]
	s_waitcnt vmcnt(0)

; __device__ __forceinline__ unsigned xb_add(unsigned* p, unsigned v) { return __hip_atomic_fetch_add(p, v, __ATOMIC_RELAXED, __HIP_MEMORY_SCOPE_AGENT); }
; __device__ __forceinline__ void xcd_barrier(const XcdBarrier& b) {
;     ...
;             __builtin_amdgcn_fence(__ATOMIC_ACQUIRE, "agent");
;             xb_add(&bar[XB_XGEN(b.x)], 1u);
;             asm volatile("s_waitcnt vmcnt(0)" ::: "memory");
.LBB0_1122:
	s_or_b64 exec, exec, s[6:7]
	s_mov_b64 s[6:7], exec
	v_mbcnt_lo_u32_b32 v0, s6, 0
	v_mbcnt_hi_u32_b32 v0, s7, v0
	v_cmp_eq_u32_e32 vcc, 0, v0
	s_waitcnt vmcnt(0)
	buffer_inv sc1
	s_and_saveexec_b64 s[8:9], vcc
	s_cbranch_execz .LBB0_1124
	s_bcnt1_i32_b64 s6, s[6:7]
	v_mov_b32_e32 v0, 0x2000
	v_mov_b32_e32 v1, s6
.LBB0_1124:
	s_or_b64 exec, exec, s[8:9]
	s_waitcnt vmcnt(0)

; __device__ __forceinline__ unsigned xb_ld(unsigned* p)              { return __hip_atomic_load(p, __ATOMIC_RELAXED, __HIP_MEMORY_SCOPE_AGENT); }
; __device__ __forceinline__ unsigned xb_add(unsigned* p, unsigned v) { return __hip_atomic_fetch_add(p, v, __ATOMIC_RELAXED, __HIP_MEMORY_SCOPE_AGENT); }
; #define XB_SPIN(cond, bar) do { unsigned _sp = 0; while (cond) { if (XB_SLEEP) __builtin_amdgcn_s_sleep(1); \
;     if ((++_sp & 255u) == 0u) { if (xb_ld(&(bar)[XB_TMO])) break; if (_sp > XB_SPIN_CAP) { atomicAdd(&(bar)[XB_TMO], 1u); break; } } } } while (0)
; __device__ __forceinline__ void xcd_barrier(const XcdBarrier& b) {
;     ...
;             const unsigned og = xb_add(&bar[XB_TOP], 1u);
;             const unsigned tg = og / nx;
;             if (og + 1u == (tg + 1u) * nx) xb_add(&bar[XB_TOPGEN], 1u);
;             else XB_SPIN(xb_ld(&bar[XB_TOPGEN]) == tg, bar);
.LBB0_1160:
	s_or_b64 exec, exec, s[8:9]
	v_cvt_f32_u32_e32 v4, v2
	s_waitcnt vmcnt(0)
	v_readfirstlane_b32 s4, v3
	v_sub_u32_e32 v3, 0, v2
	v_rcp_iflag_f32_e32 v4, v4
	v_add_u32_e32 v5, s4, v1
	v_mul_f32_e32 v4, 0x4f7ffffe, v4
	v_cvt_u32_f32_e32 v4, v4
	v_mul_lo_u32 v1, v3, v4
	v_mul_hi_u32 v1, v4, v1
	v_add_u32_e32 v1, v4, v1
	v_mul_hi_u32 v1, v5, v1
	v_mul_lo_u32 v3, v1, v2
	v_sub_u32_e32 v3, v5, v3
	v_add_u32_e32 v4, 1, v1
	v_cmp_ge_u32_e32 vcc, v3, v2
	s_nop 1
	v_cndmask_b32_e32 v1, v1, v4, vcc
	v_sub_u32_e32 v4, v3, v2
	v_cndmask_b32_e32 v3, v3, v4, vcc
	v_add_u32_e32 v4, 1, v1
	v_cmp_ge_u32_e32 vcc, v3, v2
	v_add_u32_e32 v3, 1, v5
	s_nop 0
	v_cndmask_b32_e32 v1, v1, v4, vcc
	v_mul_lo_u32 v4, v2, v1
	v_add_u32_e32 v2, v4, v2
	v_cmp_ne_u32_e32 vcc, v3, v2
	s_and_saveexec_b64 s[4:5], vcc
	s_xor_b64 s[4:5], exec, s[4:5]
	s_cbranch_execz .LBB0_1174
	s_waitcnt lgkmcnt(0)
	v_add_u32_e32 v1, 1, v1
	v_mul_lo_u32 v1, v1, v0
	s_add_u32 s12, s80, 0x3400
	s_addc_u32 s13, s81, 0
	v_mov_b32_e32 v0, 0
	global_load_dword v0, v0, s[12:13] sc1
	s_waitcnt vmcnt(0)
	v_cmp_lt_u32_e32 vcc, v0, v1
	s_and_saveexec_b64 s[8:9], vcc
	s_cbranch_execz .LBB0_1173
	s_add_u32 s10, s76, 0x60200
	s_addc_u32 s11, s77, 0
	s_mov_b32 s24, 1
	s_mov_b64 s[14:15], 0
	v_mov_b32_e32 v0, 0
	s_branch .LBB0_1164

; __device__ __forceinline__ unsigned xb_ld(unsigned* p)              { return __hip_atomic_load(p, __ATOMIC_RELAXED, __HIP_MEMORY_SCOPE_AGENT); }
; __device__ __forceinline__ unsigned xb_add(unsigned* p, unsigned v) { return __hip_atomic_fetch_add(p, v, __ATOMIC_RELAXED, __HIP_MEMORY_SCOPE_AGENT); }
; #define XB_SPIN(cond, bar) do { unsigned _sp = 0; while (cond) { if (XB_SLEEP) __builtin_amdgcn_s_sleep(1); \
;     if ((++_sp & 255u) == 0u) { if (xb_ld(&(bar)[XB_TMO])) break; if (_sp > XB_SPIN_CAP) { atomicAdd(&(bar)[XB_TMO], 1u); break; } } } } while (0)
; __device__ __forceinline__ void xcd_barrier(const XcdBarrier& b) {
;     ...
;             const unsigned og = xb_add(&bar[XB_TOP], 1u);
;             const unsigned tg = og / nx;
;             if (og + 1u == (tg + 1u) * nx) xb_add(&bar[XB_TOPGEN], 1u);
;             else XB_SPIN(xb_ld(&bar[XB_TOPGEN]) == tg, bar);
.LBB0_1177:
	s_or_b64 exec, exec, s[8:9]
	v_cvt_f32_u32_e32 v3, v0
	s_waitcnt vmcnt(0)
	v_readfirstlane_b32 s4, v2
	s_add_u32 s8, s76, 0x63500
	s_addc_u32 s9, s77, 0
	v_rcp_iflag_f32_e32 v3, v3
	v_add_u32_e32 v1, s4, v1
	v_add_u32_e32 v4, 1, v1
	s_mov_b64 s[10:11], 0
	v_mul_f32_e32 v2, 0x4f7ffffe, v3
	v_cvt_u32_f32_e32 v2, v2
	v_sub_u32_e32 v3, 0, v0
	v_mul_lo_u32 v3, v3, v2
	v_mul_hi_u32 v3, v2, v3
	v_add_u32_e32 v2, v2, v3
	v_mul_hi_u32 v2, v1, v2
	v_mul_lo_u32 v3, v2, v0
	v_sub_u32_e32 v1, v1, v3
	v_add_u32_e32 v5, 1, v2
	v_cmp_ge_u32_e32 vcc, v1, v0
	v_sub_u32_e32 v3, v1, v0
	s_nop 0
	v_cndmask_b32_e32 v2, v2, v5, vcc
	v_cndmask_b32_e32 v1, v1, v3, vcc
	v_add_u32_e32 v3, 1, v2
	v_cmp_ge_u32_e32 vcc, v1, v0
	s_nop 1
	v_cndmask_b32_e32 v2, v2, v3, vcc
	v_mul_lo_u32 v1, v0, v2
	v_add_u32_e32 v0, v1, v0
	v_cmp_ne_u32_e32 vcc, v4, v0
	v_mov_b32_e32 v254, v0
	v_mov_b64_e32 v[0:1], s[8:9]
	s_and_saveexec_b64 s[4:5], vcc
	s_cbranch_execz .LBB0_1189
	v_mov_b32_e32 v0, 0
	s_sub_u32 s98, s8, 0x100
	s_subb_u32 s99, s9, 0
	global_load_dword v1, v0, s[98:99] sc1
	s_mov_b64 s[14:15], 0
	s_waitcnt vmcnt(0)
	v_cmp_lt_u32_e32 vcc, v1, v254
	s_and_saveexec_b64 s[12:13], vcc
	s_cbranch_execz .LBB0_1188
	s_add_u32 s10, s76, 0x60200
	s_addc_u32 s11, s77, 0
	s_mov_b32 s24, 1
	s_branch .LBB0_1181

; __device__ __forceinline__ unsigned xb_add(unsigned* p, unsigned v) { return __hip_atomic_fetch_add(p, v, __ATOMIC_RELAXED, __HIP_MEMORY_SCOPE_AGENT); }
; __device__ __forceinline__ void xcd_barrier(const XcdBarrier& b) {
;     ...
;             __builtin_amdgcn_fence(__ATOMIC_ACQUIRE, "agent");
;             xb_add(&bar[XB_XGEN(b.x)], 1u);
;             asm volatile("s_waitcnt vmcnt(0)" ::: "memory");
.LBB0_1191:
	s_or_b64 exec, exec, s[4:5]
	s_mov_b64 s[4:5], exec
	v_mbcnt_lo_u32_b32 v0, s4, 0
	v_mbcnt_hi_u32_b32 v0, s5, v0
	v_cmp_eq_u32_e32 vcc, 0, v0
	s_waitcnt vmcnt(0)
	buffer_inv sc1
	s_and_saveexec_b64 s[8:9], vcc
	s_cbranch_execz .LBB0_1193
	s_bcnt1_i32_b64 s4, s[4:5]
	v_mov_b32_e32 v0, 0x2000
	v_mov_b32_e32 v1, s4
.LBB0_1193:
	s_or_b64 exec, exec, s[8:9]
	s_waitcnt vmcnt(0)

; __device__ __forceinline__ unsigned xb_add(unsigned* p, unsigned v) { return __hip_atomic_fetch_add(p, v, __ATOMIC_RELAXED, __HIP_MEMORY_SCOPE_AGENT); }
; __device__ __forceinline__ void xcd_barrier(const XcdBarrier& b) {
;     ...
;             __builtin_amdgcn_fence(__ATOMIC_ACQUIRE, "agent");
;             xb_add(&bar[XB_XGEN(b.x)], 1u);
;             asm volatile("s_waitcnt vmcnt(0)" ::: "memory");
.LBB0_1287:
	s_or_b64 exec, exec, s[4:5]
	s_mov_b64 s[4:5], exec
	v_mbcnt_lo_u32_b32 v0, s4, 0
	v_mbcnt_hi_u32_b32 v0, s5, v0
	v_cmp_eq_u32_e32 vcc, 0, v0
	s_waitcnt vmcnt(0)
	buffer_inv sc1
	s_and_saveexec_b64 s[8:9], vcc
	s_cbranch_execz .LBB0_1289
	s_bcnt1_i32_b64 s4, s[4:5]
	v_mov_b32_e32 v0, 0x2000
	v_mov_b32_e32 v1, s4
.LBB0_1289:
	s_or_b64 exec, exec, s[8:9]
	s_waitcnt vmcnt(0)

; __device__ __forceinline__ unsigned xb_add(unsigned* p, unsigned v) { return __hip_atomic_fetch_add(p, v, __ATOMIC_RELAXED, __HIP_MEMORY_SCOPE_AGENT); }
; __device__ __forceinline__ void xcd_barrier(const XcdBarrier& b) {
;     ...
;             __builtin_amdgcn_fence(__ATOMIC_ACQUIRE, "agent");
;             xb_add(&bar[XB_XGEN(b.x)], 1u);
;             asm volatile("s_waitcnt vmcnt(0)" ::: "memory");
.LBB0_1356:
	s_or_b64 exec, exec, s[4:5]
	s_mov_b64 s[4:5], exec
	v_mbcnt_lo_u32_b32 v0, s4, 0
	v_mbcnt_hi_u32_b32 v0, s5, v0
	v_cmp_eq_u32_e32 vcc, 0, v0
	s_waitcnt vmcnt(0)
	buffer_inv sc1
	s_and_saveexec_b64 s[8:9], vcc
	s_cbranch_execz .LBB0_1358
	s_bcnt1_i32_b64 s4, s[4:5]
	v_mov_b32_e32 v0, 0x2000
	v_mov_b32_e32 v1, s4
.LBB0_1358:
	s_or_b64 exec, exec, s[8:9]
	s_waitcnt vmcnt(0)

; __device__ __forceinline__ unsigned xb_add(unsigned* p, unsigned v) { return __hip_atomic_fetch_add(p, v, __ATOMIC_RELAXED, __HIP_MEMORY_SCOPE_AGENT); }
; __device__ __forceinline__ void xcd_barrier(const XcdBarrier& b) {
;     ...
;             __builtin_amdgcn_fence(__ATOMIC_ACQUIRE, "agent");
;             xb_add(&bar[XB_XGEN(b.x)], 1u);
;             asm volatile("s_waitcnt vmcnt(0)" ::: "memory");
.LBB0_1448:
	s_or_b64 exec, exec, s[4:5]
	s_mov_b64 s[4:5], exec
	v_mbcnt_lo_u32_b32 v0, s4, 0
	v_mbcnt_hi_u32_b32 v0, s5, v0
	v_cmp_eq_u32_e32 vcc, 0, v0
	s_waitcnt vmcnt(0)
	buffer_inv sc1
	s_and_saveexec_b64 s[8:9], vcc
	s_cbranch_execz .LBB0_1450
	s_bcnt1_i32_b64 s4, s[4:5]
	v_mov_b32_e32 v0, 0x2000
	v_mov_b32_e32 v1, s4
.LBB0_1450:
	s_or_b64 exec, exec, s[8:9]
	s_waitcnt vmcnt(0)

; __device__ __forceinline__ unsigned xb_add(unsigned* p, unsigned v) { return __hip_atomic_fetch_add(p, v, __ATOMIC_RELAXED, __HIP_MEMORY_SCOPE_AGENT); }
; __device__ __forceinline__ void xcd_barrier(const XcdBarrier& b) {
;     ...
;             __builtin_amdgcn_fence(__ATOMIC_ACQUIRE, "agent");
;             xb_add(&bar[XB_XGEN(b.x)], 1u);
;             asm volatile("s_waitcnt vmcnt(0)" ::: "memory");
.LBB0_1543:
	s_or_b64 exec, exec, s[4:5]
	s_mov_b64 s[4:5], exec
	v_mbcnt_lo_u32_b32 v0, s4, 0
	v_mbcnt_hi_u32_b32 v0, s5, v0
	v_cmp_eq_u32_e32 vcc, 0, v0
	s_waitcnt vmcnt(0)
	buffer_inv sc1
	s_and_saveexec_b64 s[8:9], vcc
	s_cbranch_execz .LBB0_1545
	s_bcnt1_i32_b64 s4, s[4:5]
	v_mov_b32_e32 v0, 0x2000
	v_mov_b32_e32 v1, s4
.LBB0_1545:
	s_or_b64 exec, exec, s[8:9]
	s_waitcnt vmcnt(0)

; __device__ __forceinline__ unsigned xb_add(unsigned* p, unsigned v) { return __hip_atomic_fetch_add(p, v, __ATOMIC_RELAXED, __HIP_MEMORY_SCOPE_AGENT); }
; __device__ __forceinline__ void xcd_barrier(const XcdBarrier& b) {
;     ...
;             __builtin_amdgcn_fence(__ATOMIC_ACQUIRE, "agent");
;             xb_add(&bar[XB_XGEN(b.x)], 1u);
;             asm volatile("s_waitcnt vmcnt(0)" ::: "memory");
.LBB0_1612:
	s_or_b64 exec, exec, s[4:5]
	s_mov_b64 s[4:5], exec
	v_mbcnt_lo_u32_b32 v0, s4, 0
	v_mbcnt_hi_u32_b32 v0, s5, v0
	v_cmp_eq_u32_e32 vcc, 0, v0
	s_waitcnt vmcnt(0)
	buffer_inv sc1
	s_and_saveexec_b64 s[6:7], vcc
	s_cbranch_execz .LBB0_1614
	s_bcnt1_i32_b64 s4, s[4:5]
	v_mov_b32_e32 v0, 0x2000
	v_mov_b32_e32 v1, s4
.LBB0_1614:
	s_or_b64 exec, exec, s[6:7]
	s_waitcnt vmcnt(0)
